# K-loop load clusters trimmed: LDS reads separate m0 writes from DMAs (no s_nop), merged LB waits; otherwise same as v49
# speedup vs baseline: 1.0061x; 1.0061x over previous
; #define PG8_STAGE(bufoff, gbase, voff) do { _Pragma("unroll") for (int _i = 0; _i < 2; ++_i) \
;         __builtin_amdgcn_global_load_lds((const unsigned*)((const char*)(gbase) + (voff)[_i]), (LAS unsigned*)(lds + (bufoff) + ldsw + _i * 8192), 16, 0, 0); } while (0)
; #define PG8_LDA(dst, b, h) do { _Pragma("unroll") for (int m = 0; m < 4; ++m) _Pragma("unroll") for (int k = 0; k < 2; ++k) dst[m][k] = *(const LAS bf16x8*)(lds + PG8_SA(b, h) + aoff + m * 2048 + k * 1024); } while (0)
; #define PG8_WAIT_V(n) asm volatile("s_waitcnt vmcnt(" #n ")" ::: "memory")
; #define PG8_WAIT_L(n) asm volatile("s_waitcnt lgkmcnt(" #n ")" ::: "memory")
; template <class Prog>
; __device__ __forceinline__ void gemm_phase(LAS unsigned char* lds, const int K, const Prog& S) {
;     ...
;         for (int t = 0; t < nt; t += 2) {
;             const bool last = (t == nt - 2);
;             const char* a1 = cA + (size_t)(t + 1) * kstep;
;             const char* a2 = last ? nA : cA + (size_t)(t + 2) * kstep; const char* b2 = last ? nB : cB + (size_t)(t + 2) * kstep;
;             const char* a3 = a2 + kstep; const char* b3 = b2 + kstep;
;             PG8_LDB(B0, 0, 0); PG8_SCHED; PG8_LDA(At, 0, 0); PG8_STAGE(PG8_SA(1, 1), a1 + hstep, voffA);
;             PG8_WAIT_L(8); PG8_BAR; PG8_WAIT_L(0); PG8_MMA(0, 0, At, B0); PG8_BAR; PG8_SCHED;
;             PG8_LDB(B1, 0, 1); PG8_STAGE(PG8_SB(0, 0), b2, voffB);
;             PG8_BAR; PG8_WAIT_L(0); PG8_MMA(0, 1, At, B1); PG8_BAR;
;             PG8_LDA(At, 0, 1); PG8_STAGE(PG8_SA(0, 0), a2, voffA);
;             PG8_BAR; PG8_WAIT_L(0); PG8_MMA(1, 0, At, B0); PG8_BAR; PG8_SCHED;
;             PG8_STAGE(PG8_SB(0, 1), b2 + hstep, voffB);
;             PG8_WAIT_V(6); PG8_BAR; PG8_MMA(1, 1, At, B1); PG8_BAR;
;             PG8_LDB(B0, 1, 0); PG8_SCHED; PG8_LDA(At, 1, 0); PG8_STAGE(PG8_SA(0, 1), a2 + hstep, voffA);
;             PG8_WAIT_L(8); PG8_BAR; PG8_WAIT_L(0); PG8_MMA(0, 0, At, B0); PG8_BAR; PG8_SCHED;
;             PG8_LDB(B1, 1, 1); PG8_STAGE(PG8_SB(1, 0), b3, voffB);
;             PG8_BAR; PG8_WAIT_L(0); PG8_MMA(0, 1, At, B1); PG8_BAR;
;             PG8_LDA(At, 1, 1); PG8_STAGE(PG8_SA(1, 0), a3, voffA);
;             PG8_BAR; PG8_WAIT_L(0); PG8_MMA(1, 0, At, B0); PG8_BAR; PG8_SCHED;
;             PG8_STAGE(PG8_SB(1, 1), b3 + hstep, voffB);
;             PG8_WAIT_V(6); PG8_BAR; PG8_MMA(1, 1, At, B1); PG8_BAR;
.LBB0_100:
	s_add_u32 s40, s40, 0x80080
	s_addc_u32 s41, s41, 0
	s_add_u32 s9, s44, 0x100
	s_addc_u32 s15, s45, 0
	s_mov_b32 s69, -2
	s_waitcnt vmcnt(16)
	v_add_u32_e32 v244, 0x10000, v205
	s_add_u32 s44, s40, 0xfff80080
	s_addc_u32 s45, s41, -1
	s_cmp_eq_u32 s69, 28
	s_cselect_b32 s47, s5, s45
	s_cselect_b32 s46, s4, s44
	s_cselect_b32 s45, s13, s15
	s_cselect_b32 s44, s12, s9
	s_add_u32 s76, s40, 0xfff80000
	s_addc_u32 s77, s41, -1
	ds_read_b128 v[128:131], v244
	ds_read_b128 v[132:135], v244 offset:1024
	ds_read_b128 v[136:139], v244 offset:2048
	ds_read_b128 v[140:143], v244 offset:3072
	s_add_i32 m0, s92, 0x8000
	ds_read_b128 v[188:191], v244 offset:16384
	ds_read_b128 v[196:199], v244 offset:17408
	ds_read_b128 v[200:203], v244 offset:18432
	ds_read_b128 v[218:221], v244 offset:19456
	global_load_lds_dwordx4 v184, s[76:77]
	s_add_i32 m0, s92, 0xa000
	ds_read_b128 v[144:147], v216
	ds_read_b128 v[148:151], v216 offset:1024
	ds_read_b128 v[152:155], v216 offset:2048
	ds_read_b128 v[156:159], v216 offset:3072
	global_load_lds_dwordx4 v186, s[76:77]
	s_add_i32 m0, s92, 0xc000
	ds_read_b128 v[160:163], v216 offset:4096
	ds_read_b128 v[164:167], v216 offset:5120
	ds_read_b128 v[168:171], v216 offset:6144
	global_load_lds_dwordx4 v184, s[40:41]
	s_add_i32 m0, s92, 0xe000
	ds_read_b128 v[172:175], v216 offset:7168
	global_load_lds_dwordx4 v186, s[40:41]
	s_waitcnt lgkmcnt(0)
	s_barrier
	v_mfma_f32_16x16x32_bf16 v[124:127], v[128:131], v[144:147], 0
	v_mfma_f32_16x16x32_bf16 v[116:119], v[136:139], v[144:147], 0
	v_mfma_f32_16x16x32_bf16 v[108:111], v[128:131], v[152:155], 0
	v_mfma_f32_16x16x32_bf16 v[100:103], v[136:139], v[152:155], 0
	v_mfma_f32_16x16x32_bf16 v[92:95], v[128:131], v[160:163], 0
	v_mfma_f32_16x16x32_bf16 v[84:87], v[136:139], v[160:163], 0
	v_mfma_f32_16x16x32_bf16 v[76:79], v[128:131], v[168:171], 0
	v_mfma_f32_16x16x32_bf16 v[68:71], v[136:139], v[168:171], 0
	v_mfma_f32_16x16x32_bf16 v[124:127], v[132:135], v[148:151], v[124:127]
	v_mfma_f32_16x16x32_bf16 v[116:119], v[140:143], v[148:151], v[116:119]
	v_mfma_f32_16x16x32_bf16 v[108:111], v[132:135], v[156:159], v[108:111]
	v_mfma_f32_16x16x32_bf16 v[100:103], v[140:143], v[156:159], v[100:103]
	v_mfma_f32_16x16x32_bf16 v[92:95], v[132:135], v[164:167], v[92:95]
	v_mfma_f32_16x16x32_bf16 v[84:87], v[140:143], v[164:167], v[84:87]
	v_mfma_f32_16x16x32_bf16 v[76:79], v[132:135], v[172:175], v[76:79]
	v_mfma_f32_16x16x32_bf16 v[68:71], v[140:143], v[172:175], v[68:71]
	v_mfma_f32_16x16x32_bf16 v[120:123], v[188:191], v[144:147], 0
	v_mfma_f32_16x16x32_bf16 v[112:115], v[200:203], v[144:147], 0
	v_mfma_f32_16x16x32_bf16 v[104:107], v[188:191], v[152:155], 0
	v_mfma_f32_16x16x32_bf16 v[96:99], v[200:203], v[152:155], 0
	v_mfma_f32_16x16x32_bf16 v[88:91], v[188:191], v[160:163], 0
	v_mfma_f32_16x16x32_bf16 v[80:83], v[200:203], v[160:163], 0
	v_mfma_f32_16x16x32_bf16 v[72:75], v[188:191], v[168:171], 0
	v_mfma_f32_16x16x32_bf16 v[64:67], v[200:203], v[168:171], 0
	v_mfma_f32_16x16x32_bf16 v[120:123], v[196:199], v[148:151], v[120:123]
	v_mfma_f32_16x16x32_bf16 v[112:115], v[218:221], v[148:151], v[112:115]
	v_mfma_f32_16x16x32_bf16 v[104:107], v[196:199], v[156:159], v[104:107]
	v_mfma_f32_16x16x32_bf16 v[96:99], v[218:221], v[156:159], v[96:99]
	v_mfma_f32_16x16x32_bf16 v[88:91], v[196:199], v[164:167], v[88:91]
	v_mfma_f32_16x16x32_bf16 v[80:83], v[218:221], v[164:167], v[80:83]
	v_mfma_f32_16x16x32_bf16 v[72:75], v[196:199], v[172:175], v[72:75]
	v_mfma_f32_16x16x32_bf16 v[64:67], v[218:221], v[172:175], v[64:67]
	s_barrier
	s_add_i32 m0, s92, 0x10000
	ds_read_b128 v[144:147], v216 offset:16384
	ds_read_b128 v[148:151], v216 offset:17408
	global_load_lds_dwordx4 v192, s[44:45]
	s_add_i32 m0, s92, 0x12000
	ds_read_b128 v[152:155], v216 offset:18432
	ds_read_b128 v[156:159], v216 offset:19456
	global_load_lds_dwordx4 v180, s[44:45]
	s_add_i32 m0, s92, 0x14000
	s_add_u32 s76, s44, 0x80000
	s_addc_u32 s77, s45, 0
	ds_read_b128 v[160:163], v216 offset:20480
	ds_read_b128 v[164:167], v216 offset:21504
	global_load_lds_dwordx4 v192, s[76:77]
	s_add_i32 m0, s92, 0x16000
	ds_read_b128 v[168:171], v216 offset:22528
	ds_read_b128 v[172:175], v216 offset:23552
	global_load_lds_dwordx4 v180, s[76:77]
	s_waitcnt vmcnt(4) lgkmcnt(0)
	s_barrier
	v_mfma_f32_16x16x32_bf16 v[60:63], v[128:131], v[144:147], 0
	v_mfma_f32_16x16x32_bf16 v[52:55], v[136:139], v[144:147], 0
	v_mfma_f32_16x16x32_bf16 v[44:47], v[128:131], v[152:155], 0
	v_mfma_f32_16x16x32_bf16 v[36:39], v[136:139], v[152:155], 0
	v_mfma_f32_16x16x32_bf16 v[28:31], v[128:131], v[160:163], 0
	v_mfma_f32_16x16x32_bf16 v[20:23], v[136:139], v[160:163], 0
	v_mfma_f32_16x16x32_bf16 v[12:15], v[128:131], v[168:171], 0
	v_mfma_f32_16x16x32_bf16 v[4:7], v[136:139], v[168:171], 0
	v_mfma_f32_16x16x32_bf16 v[60:63], v[132:135], v[148:151], v[60:63]
	v_mfma_f32_16x16x32_bf16 v[52:55], v[140:143], v[148:151], v[52:55]
	v_mfma_f32_16x16x32_bf16 v[44:47], v[132:135], v[156:159], v[44:47]
	v_mfma_f32_16x16x32_bf16 v[36:39], v[140:143], v[156:159], v[36:39]
	v_mfma_f32_16x16x32_bf16 v[28:31], v[132:135], v[164:167], v[28:31]
	v_mfma_f32_16x16x32_bf16 v[20:23], v[140:143], v[164:167], v[20:23]
	v_mfma_f32_16x16x32_bf16 v[12:15], v[132:135], v[172:175], v[12:15]
	v_mfma_f32_16x16x32_bf16 v[4:7], v[140:143], v[172:175], v[4:7]
	v_mfma_f32_16x16x32_bf16 v[56:59], v[188:191], v[144:147], 0
	v_mfma_f32_16x16x32_bf16 v[48:51], v[200:203], v[144:147], 0
	v_mfma_f32_16x16x32_bf16 v[40:43], v[188:191], v[152:155], 0
	v_mfma_f32_16x16x32_bf16 v[32:35], v[200:203], v[152:155], 0
	v_mfma_f32_16x16x32_bf16 v[24:27], v[188:191], v[160:163], 0
	v_mfma_f32_16x16x32_bf16 v[16:19], v[200:203], v[160:163], 0
	v_mfma_f32_16x16x32_bf16 v[8:11], v[188:191], v[168:171], 0
	v_mfma_f32_16x16x32_bf16 v[0:3], v[200:203], v[168:171], 0
	v_mfma_f32_16x16x32_bf16 v[56:59], v[196:199], v[148:151], v[56:59]
	v_mfma_f32_16x16x32_bf16 v[48:51], v[218:221], v[148:151], v[48:51]
	v_mfma_f32_16x16x32_bf16 v[40:43], v[196:199], v[156:159], v[40:43]
	v_mfma_f32_16x16x32_bf16 v[32:35], v[218:221], v[156:159], v[32:35]
	v_mfma_f32_16x16x32_bf16 v[24:27], v[196:199], v[164:167], v[24:27]
	v_mfma_f32_16x16x32_bf16 v[16:19], v[218:221], v[164:167], v[16:19]
	v_mfma_f32_16x16x32_bf16 v[8:11], v[196:199], v[172:175], v[8:11]
	v_mfma_f32_16x16x32_bf16 v[0:3], v[218:221], v[172:175], v[0:3]
	s_barrier
; #define PG8_STAGE(bufoff, gbase, voff) do { _Pragma("unroll") for (int _i = 0; _i < 2; ++_i) \
;         __builtin_amdgcn_global_load_lds((const unsigned*)((const char*)(gbase) + (voff)[_i]), (LAS unsigned*)(lds + (bufoff) + ldsw + _i * 8192), 16, 0, 0); } while (0)
; #define PG8_LDA(dst, b, h) do { _Pragma("unroll") for (int m = 0; m < 4; ++m) _Pragma("unroll") for (int k = 0; k < 2; ++k) dst[m][k] = *(const LAS bf16x8*)(lds + PG8_SA(b, h) + aoff + m * 2048 + k * 1024); } while (0)
; #define PG8_WAIT_V(n) asm volatile("s_waitcnt vmcnt(" #n ")" ::: "memory")
; #define PG8_WAIT_L(n) asm volatile("s_waitcnt lgkmcnt(" #n ")" ::: "memory")
; template <class Prog>
; __device__ __forceinline__ void gemm_phase(LAS unsigned char* lds, const int K, const Prog& S) {
;     ...
;         for (int t = 0; t < nt; t += 2) {
;             const bool last = (t == nt - 2);
;             const char* a1 = cA + (size_t)(t + 1) * kstep;
;             const char* a2 = last ? nA : cA + (size_t)(t + 2) * kstep; const char* b2 = last ? nB : cB + (size_t)(t + 2) * kstep;
;             const char* a3 = a2 + kstep; const char* b3 = b2 + kstep;
;             PG8_LDB(B0, 0, 0); PG8_SCHED; PG8_LDA(At, 0, 0); PG8_STAGE(PG8_SA(1, 1), a1 + hstep, voffA);
;             PG8_WAIT_L(8); PG8_BAR; PG8_WAIT_L(0); PG8_MMA(0, 0, At, B0); PG8_BAR; PG8_SCHED;
;             PG8_LDB(B1, 0, 1); PG8_STAGE(PG8_SB(0, 0), b2, voffB);
;             PG8_BAR; PG8_WAIT_L(0); PG8_MMA(0, 1, At, B1); PG8_BAR;
;             PG8_LDA(At, 0, 1); PG8_STAGE(PG8_SA(0, 0), a2, voffA);
;             PG8_BAR; PG8_WAIT_L(0); PG8_MMA(1, 0, At, B0); PG8_BAR; PG8_SCHED;
;             PG8_STAGE(PG8_SB(0, 1), b2 + hstep, voffB);
;             PG8_WAIT_V(6); PG8_BAR; PG8_MMA(1, 1, At, B1); PG8_BAR;
;             PG8_LDB(B0, 1, 0); PG8_SCHED; PG8_LDA(At, 1, 0); PG8_STAGE(PG8_SA(0, 1), a2 + hstep, voffA);
;             PG8_WAIT_L(8); PG8_BAR; PG8_WAIT_L(0); PG8_MMA(0, 0, At, B0); PG8_BAR; PG8_SCHED;
;             PG8_LDB(B1, 1, 1); PG8_STAGE(PG8_SB(1, 0), b3, voffB);
;             PG8_BAR; PG8_WAIT_L(0); PG8_MMA(0, 1, At, B1); PG8_BAR;
;             PG8_LDA(At, 1, 1); PG8_STAGE(PG8_SA(1, 0), a3, voffA);
;             PG8_BAR; PG8_WAIT_L(0); PG8_MMA(1, 0, At, B0); PG8_BAR; PG8_SCHED;
;             PG8_STAGE(PG8_SB(1, 1), b3 + hstep, voffB);
;             PG8_WAIT_V(6); PG8_BAR; PG8_MMA(1, 1, At, B1); PG8_BAR;
	s_add_u32 s98, s46, 0x80000
	s_addc_u32 s99, s47, 0
	ds_read_b128 v[128:131], v244 offset:32768
	ds_read_b128 v[132:135], v244 offset:33792
	ds_read_b128 v[136:139], v244 offset:34816
	ds_read_b128 v[140:143], v244 offset:35840
	s_mov_b32 m0, s92
	ds_read_b128 v[188:191], v244 offset:49152
	ds_read_b128 v[196:199], v244 offset:50176
	ds_read_b128 v[200:203], v244 offset:51200
	ds_read_b128 v[218:221], v244 offset:52224
	global_load_lds_dwordx4 v176, s[46:47]
	s_add_i32 m0, s92, 0x2000
	ds_read_b128 v[144:147], v216 offset:32768
	ds_read_b128 v[148:151], v216 offset:33792
	ds_read_b128 v[152:155], v216 offset:34816
	ds_read_b128 v[156:159], v216 offset:35840
	global_load_lds_dwordx4 v178, s[46:47]
	s_add_i32 m0, s92, 0x4000
	ds_read_b128 v[160:163], v216 offset:36864
	ds_read_b128 v[164:167], v216 offset:37888
	ds_read_b128 v[168:171], v216 offset:38912
	global_load_lds_dwordx4 v176, s[98:99]
	s_add_i32 m0, s92, 0x6000
	ds_read_b128 v[172:175], v216 offset:39936
	global_load_lds_dwordx4 v178, s[98:99]
	s_waitcnt lgkmcnt(0)
	s_barrier
	v_mfma_f32_16x16x32_bf16 v[124:127], v[128:131], v[144:147], v[124:127]
	v_mfma_f32_16x16x32_bf16 v[116:119], v[136:139], v[144:147], v[116:119]
	v_mfma_f32_16x16x32_bf16 v[108:111], v[128:131], v[152:155], v[108:111]
	v_mfma_f32_16x16x32_bf16 v[100:103], v[136:139], v[152:155], v[100:103]
	v_mfma_f32_16x16x32_bf16 v[92:95], v[128:131], v[160:163], v[92:95]
	v_mfma_f32_16x16x32_bf16 v[84:87], v[136:139], v[160:163], v[84:87]
	v_mfma_f32_16x16x32_bf16 v[76:79], v[128:131], v[168:171], v[76:79]
	v_mfma_f32_16x16x32_bf16 v[68:71], v[136:139], v[168:171], v[68:71]
	v_mfma_f32_16x16x32_bf16 v[124:127], v[132:135], v[148:151], v[124:127]
	v_mfma_f32_16x16x32_bf16 v[116:119], v[140:143], v[148:151], v[116:119]
	v_mfma_f32_16x16x32_bf16 v[108:111], v[132:135], v[156:159], v[108:111]
	v_mfma_f32_16x16x32_bf16 v[100:103], v[140:143], v[156:159], v[100:103]
	v_mfma_f32_16x16x32_bf16 v[92:95], v[132:135], v[164:167], v[92:95]
	v_mfma_f32_16x16x32_bf16 v[84:87], v[140:143], v[164:167], v[84:87]
	v_mfma_f32_16x16x32_bf16 v[76:79], v[132:135], v[172:175], v[76:79]
	v_mfma_f32_16x16x32_bf16 v[68:71], v[140:143], v[172:175], v[68:71]
	v_mfma_f32_16x16x32_bf16 v[120:123], v[188:191], v[144:147], v[120:123]
	v_mfma_f32_16x16x32_bf16 v[112:115], v[200:203], v[144:147], v[112:115]
	v_mfma_f32_16x16x32_bf16 v[104:107], v[188:191], v[152:155], v[104:107]
	v_mfma_f32_16x16x32_bf16 v[96:99], v[200:203], v[152:155], v[96:99]
	v_mfma_f32_16x16x32_bf16 v[88:91], v[188:191], v[160:163], v[88:91]
	v_mfma_f32_16x16x32_bf16 v[80:83], v[200:203], v[160:163], v[80:83]
	v_mfma_f32_16x16x32_bf16 v[72:75], v[188:191], v[168:171], v[72:75]
	v_mfma_f32_16x16x32_bf16 v[64:67], v[200:203], v[168:171], v[64:67]
	v_mfma_f32_16x16x32_bf16 v[120:123], v[196:199], v[148:151], v[120:123]
	v_mfma_f32_16x16x32_bf16 v[112:115], v[218:221], v[148:151], v[112:115]
	v_mfma_f32_16x16x32_bf16 v[104:107], v[196:199], v[156:159], v[104:107]
	v_mfma_f32_16x16x32_bf16 v[96:99], v[218:221], v[156:159], v[96:99]
	v_mfma_f32_16x16x32_bf16 v[88:91], v[196:199], v[164:167], v[88:91]
	v_mfma_f32_16x16x32_bf16 v[80:83], v[218:221], v[164:167], v[80:83]
	v_mfma_f32_16x16x32_bf16 v[72:75], v[196:199], v[172:175], v[72:75]
	v_mfma_f32_16x16x32_bf16 v[64:67], v[218:221], v[172:175], v[64:67]
	s_barrier
	s_add_u32 s98, s44, 0x80
	s_addc_u32 s99, s45, 0
	s_add_i32 m0, s92, 0x18000
	ds_read_b128 v[144:147], v216 offset:49152
	ds_read_b128 v[148:151], v216 offset:50176
	global_load_lds_dwordx4 v192, s[98:99]
	s_add_i32 m0, s92, 0x1a000
	ds_read_b128 v[152:155], v216 offset:51200
	ds_read_b128 v[156:159], v216 offset:52224
	global_load_lds_dwordx4 v180, s[98:99]
	s_add_i32 m0, s92, 0x1c000
	s_add_u32 s76, s44, 0x80080
	s_addc_u32 s77, s45, 0
	ds_read_b128 v[160:163], v216 offset:53248
	ds_read_b128 v[164:167], v216 offset:54272
	global_load_lds_dwordx4 v192, s[76:77]
	s_add_i32 m0, s92, 0x1e000
	ds_read_b128 v[168:171], v216 offset:55296
	ds_read_b128 v[172:175], v216 offset:56320
	global_load_lds_dwordx4 v180, s[76:77]
	s_waitcnt vmcnt(4) lgkmcnt(0)
	s_barrier
	v_mfma_f32_16x16x32_bf16 v[60:63], v[128:131], v[144:147], v[60:63]
	v_mfma_f32_16x16x32_bf16 v[52:55], v[136:139], v[144:147], v[52:55]
	v_mfma_f32_16x16x32_bf16 v[44:47], v[128:131], v[152:155], v[44:47]
	v_mfma_f32_16x16x32_bf16 v[36:39], v[136:139], v[152:155], v[36:39]
	v_mfma_f32_16x16x32_bf16 v[28:31], v[128:131], v[160:163], v[28:31]
	v_mfma_f32_16x16x32_bf16 v[20:23], v[136:139], v[160:163], v[20:23]
	v_mfma_f32_16x16x32_bf16 v[12:15], v[128:131], v[168:171], v[12:15]
	v_mfma_f32_16x16x32_bf16 v[4:7], v[136:139], v[168:171], v[4:7]
	v_mfma_f32_16x16x32_bf16 v[60:63], v[132:135], v[148:151], v[60:63]
	v_mfma_f32_16x16x32_bf16 v[52:55], v[140:143], v[148:151], v[52:55]
	v_mfma_f32_16x16x32_bf16 v[44:47], v[132:135], v[156:159], v[44:47]
	v_mfma_f32_16x16x32_bf16 v[36:39], v[140:143], v[156:159], v[36:39]
	v_mfma_f32_16x16x32_bf16 v[28:31], v[132:135], v[164:167], v[28:31]
	v_mfma_f32_16x16x32_bf16 v[20:23], v[140:143], v[164:167], v[20:23]
	v_mfma_f32_16x16x32_bf16 v[12:15], v[132:135], v[172:175], v[12:15]
	v_mfma_f32_16x16x32_bf16 v[4:7], v[140:143], v[172:175], v[4:7]
	v_mfma_f32_16x16x32_bf16 v[56:59], v[188:191], v[144:147], v[56:59]
	v_mfma_f32_16x16x32_bf16 v[48:51], v[200:203], v[144:147], v[48:51]
	v_mfma_f32_16x16x32_bf16 v[40:43], v[188:191], v[152:155], v[40:43]
	v_mfma_f32_16x16x32_bf16 v[32:35], v[200:203], v[152:155], v[32:35]
	v_mfma_f32_16x16x32_bf16 v[24:27], v[188:191], v[160:163], v[24:27]
	v_mfma_f32_16x16x32_bf16 v[16:19], v[200:203], v[160:163], v[16:19]
	v_mfma_f32_16x16x32_bf16 v[8:11], v[188:191], v[168:171], v[8:11]
	v_mfma_f32_16x16x32_bf16 v[0:3], v[200:203], v[168:171], v[0:3]
	v_mfma_f32_16x16x32_bf16 v[56:59], v[196:199], v[148:151], v[56:59]
	v_mfma_f32_16x16x32_bf16 v[48:51], v[218:221], v[148:151], v[48:51]
	v_mfma_f32_16x16x32_bf16 v[40:43], v[196:199], v[156:159], v[40:43]
	v_mfma_f32_16x16x32_bf16 v[32:35], v[218:221], v[156:159], v[32:35]
	v_mfma_f32_16x16x32_bf16 v[24:27], v[196:199], v[164:167], v[24:27]
	v_mfma_f32_16x16x32_bf16 v[16:19], v[218:221], v[164:167], v[16:19]
	v_mfma_f32_16x16x32_bf16 v[8:11], v[196:199], v[172:175], v[8:11]
	v_mfma_f32_16x16x32_bf16 v[0:3], v[218:221], v[172:175], v[0:3]
	s_add_i32 s69, s69, 2
	s_add_u32 s40, s40, 0x100
	s_addc_u32 s41, s41, 0
	s_add_u32 s9, s9, 0x100
	s_addc_u32 s15, s15, 0
	s_cmp_gt_u32 s69, 29
	s_barrier
	.p2align 6
; #define PG8_STAGE(bufoff, gbase, voff) do { _Pragma("unroll") for (int _i = 0; _i < 2; ++_i) \
;         __builtin_amdgcn_global_load_lds((const unsigned*)((const char*)(gbase) + (voff)[_i]), (LAS unsigned*)(lds + (bufoff) + ldsw + _i * 8192), 16, 0, 0); } while (0)
; #define PG8_LDA(dst, b, h) do { _Pragma("unroll") for (int m = 0; m < 4; ++m) _Pragma("unroll") for (int k = 0; k < 2; ++k) dst[m][k] = *(const LAS bf16x8*)(lds + PG8_SA(b, h) + aoff + m * 2048 + k * 1024); } while (0)
; #define PG8_WAIT_V(n) asm volatile("s_waitcnt vmcnt(" #n ")" ::: "memory")
; #define PG8_WAIT_L(n) asm volatile("s_waitcnt lgkmcnt(" #n ")" ::: "memory")
; template <class Prog>
; __device__ __forceinline__ void gemm_phase(LAS unsigned char* lds, const int K, const Prog& S) {
;     ...
;         for (int t = 0; t < nt; t += 2) {
;             const bool last = (t == nt - 2);
;             const char* a1 = cA + (size_t)(t + 1) * kstep;
;             const char* a2 = last ? nA : cA + (size_t)(t + 2) * kstep; const char* b2 = last ? nB : cB + (size_t)(t + 2) * kstep;
;             const char* a3 = a2 + kstep; const char* b3 = b2 + kstep;
;             PG8_LDB(B0, 0, 0); PG8_SCHED; PG8_LDA(At, 0, 0); PG8_STAGE(PG8_SA(1, 1), a1 + hstep, voffA);
;             PG8_WAIT_L(8); PG8_BAR; PG8_WAIT_L(0); PG8_MMA(0, 0, At, B0); PG8_BAR; PG8_SCHED;
;             PG8_LDB(B1, 0, 1); PG8_STAGE(PG8_SB(0, 0), b2, voffB);
;             PG8_BAR; PG8_WAIT_L(0); PG8_MMA(0, 1, At, B1); PG8_BAR;
;             PG8_LDA(At, 0, 1); PG8_STAGE(PG8_SA(0, 0), a2, voffA);
;             PG8_BAR; PG8_WAIT_L(0); PG8_MMA(1, 0, At, B0); PG8_BAR; PG8_SCHED;
;             PG8_STAGE(PG8_SB(0, 1), b2 + hstep, voffB);
;             PG8_WAIT_V(6); PG8_BAR; PG8_MMA(1, 1, At, B1); PG8_BAR;
;             PG8_LDB(B0, 1, 0); PG8_SCHED; PG8_LDA(At, 1, 0); PG8_STAGE(PG8_SA(0, 1), a2 + hstep, voffA);
;             PG8_WAIT_L(8); PG8_BAR; PG8_WAIT_L(0); PG8_MMA(0, 0, At, B0); PG8_BAR; PG8_SCHED;
;             PG8_LDB(B1, 1, 1); PG8_STAGE(PG8_SB(1, 0), b3, voffB);
;             PG8_BAR; PG8_WAIT_L(0); PG8_MMA(0, 1, At, B1); PG8_BAR;
;             PG8_LDA(At, 1, 1); PG8_STAGE(PG8_SA(1, 0), a3, voffA);
;             PG8_BAR; PG8_WAIT_L(0); PG8_MMA(1, 0, At, B0); PG8_BAR; PG8_SCHED;
;             PG8_STAGE(PG8_SB(1, 1), b3 + hstep, voffB);
;             PG8_WAIT_V(6); PG8_BAR; PG8_MMA(1, 1, At, B1); PG8_BAR;
.LBB0_101:
	s_add_u32 s44, s40, 0xfff80080
	s_addc_u32 s45, s41, -1
	s_cmp_eq_u32 s69, 28
	s_cselect_b32 s47, s5, s45
	s_cselect_b32 s46, s4, s44
	s_cselect_b32 s45, s13, s15
	s_cselect_b32 s44, s12, s9
	s_add_u32 s76, s40, 0xfff80000
	s_addc_u32 s77, s41, -1
	ds_read_b128 v[128:131], v244
	ds_read_b128 v[132:135], v244 offset:1024
	ds_read_b128 v[136:139], v244 offset:2048
	ds_read_b128 v[140:143], v244 offset:3072
	s_add_i32 m0, s92, 0x8000
	ds_read_b128 v[188:191], v244 offset:16384
	ds_read_b128 v[196:199], v244 offset:17408
	ds_read_b128 v[200:203], v244 offset:18432
	ds_read_b128 v[218:221], v244 offset:19456
	global_load_lds_dwordx4 v184, s[76:77]
	s_add_i32 m0, s92, 0xa000
	ds_read_b128 v[144:147], v216
	ds_read_b128 v[148:151], v216 offset:1024
	ds_read_b128 v[152:155], v216 offset:2048
	ds_read_b128 v[156:159], v216 offset:3072
	global_load_lds_dwordx4 v186, s[76:77]
	s_add_i32 m0, s92, 0xc000
	ds_read_b128 v[160:163], v216 offset:4096
	ds_read_b128 v[164:167], v216 offset:5120
	ds_read_b128 v[168:171], v216 offset:6144
	global_load_lds_dwordx4 v184, s[40:41]
	s_add_i32 m0, s92, 0xe000
	ds_read_b128 v[172:175], v216 offset:7168
	global_load_lds_dwordx4 v186, s[40:41]
	s_waitcnt lgkmcnt(0)
	s_barrier
	v_mfma_f32_16x16x32_bf16 v[124:127], v[128:131], v[144:147], v[124:127]
	v_mfma_f32_16x16x32_bf16 v[116:119], v[136:139], v[144:147], v[116:119]
	v_mfma_f32_16x16x32_bf16 v[108:111], v[128:131], v[152:155], v[108:111]
	v_mfma_f32_16x16x32_bf16 v[100:103], v[136:139], v[152:155], v[100:103]
	v_mfma_f32_16x16x32_bf16 v[92:95], v[128:131], v[160:163], v[92:95]
	v_mfma_f32_16x16x32_bf16 v[84:87], v[136:139], v[160:163], v[84:87]
	v_mfma_f32_16x16x32_bf16 v[76:79], v[128:131], v[168:171], v[76:79]
	v_mfma_f32_16x16x32_bf16 v[68:71], v[136:139], v[168:171], v[68:71]
	v_mfma_f32_16x16x32_bf16 v[124:127], v[132:135], v[148:151], v[124:127]
	v_mfma_f32_16x16x32_bf16 v[116:119], v[140:143], v[148:151], v[116:119]
	v_mfma_f32_16x16x32_bf16 v[108:111], v[132:135], v[156:159], v[108:111]
	v_mfma_f32_16x16x32_bf16 v[100:103], v[140:143], v[156:159], v[100:103]
	v_mfma_f32_16x16x32_bf16 v[92:95], v[132:135], v[164:167], v[92:95]
	v_mfma_f32_16x16x32_bf16 v[84:87], v[140:143], v[164:167], v[84:87]
	v_mfma_f32_16x16x32_bf16 v[76:79], v[132:135], v[172:175], v[76:79]
	v_mfma_f32_16x16x32_bf16 v[68:71], v[140:143], v[172:175], v[68:71]
	v_mfma_f32_16x16x32_bf16 v[120:123], v[188:191], v[144:147], v[120:123]
	v_mfma_f32_16x16x32_bf16 v[112:115], v[200:203], v[144:147], v[112:115]
	v_mfma_f32_16x16x32_bf16 v[104:107], v[188:191], v[152:155], v[104:107]
	v_mfma_f32_16x16x32_bf16 v[96:99], v[200:203], v[152:155], v[96:99]
	v_mfma_f32_16x16x32_bf16 v[88:91], v[188:191], v[160:163], v[88:91]
	v_mfma_f32_16x16x32_bf16 v[80:83], v[200:203], v[160:163], v[80:83]
	v_mfma_f32_16x16x32_bf16 v[72:75], v[188:191], v[168:171], v[72:75]
	v_mfma_f32_16x16x32_bf16 v[64:67], v[200:203], v[168:171], v[64:67]
	v_mfma_f32_16x16x32_bf16 v[120:123], v[196:199], v[148:151], v[120:123]
	v_mfma_f32_16x16x32_bf16 v[112:115], v[218:221], v[148:151], v[112:115]
	v_mfma_f32_16x16x32_bf16 v[104:107], v[196:199], v[156:159], v[104:107]
	v_mfma_f32_16x16x32_bf16 v[96:99], v[218:221], v[156:159], v[96:99]
	v_mfma_f32_16x16x32_bf16 v[88:91], v[196:199], v[164:167], v[88:91]
	v_mfma_f32_16x16x32_bf16 v[80:83], v[218:221], v[164:167], v[80:83]
	v_mfma_f32_16x16x32_bf16 v[72:75], v[196:199], v[172:175], v[72:75]
	v_mfma_f32_16x16x32_bf16 v[64:67], v[218:221], v[172:175], v[64:67]
	s_barrier
	s_add_i32 m0, s92, 0x10000
	ds_read_b128 v[144:147], v216 offset:16384
	ds_read_b128 v[148:151], v216 offset:17408
	global_load_lds_dwordx4 v192, s[44:45]
	s_add_i32 m0, s92, 0x12000
	ds_read_b128 v[152:155], v216 offset:18432
	ds_read_b128 v[156:159], v216 offset:19456
	global_load_lds_dwordx4 v180, s[44:45]
	s_add_i32 m0, s92, 0x14000
	s_add_u32 s76, s44, 0x80000
	s_addc_u32 s77, s45, 0
	ds_read_b128 v[160:163], v216 offset:20480
	ds_read_b128 v[164:167], v216 offset:21504
	global_load_lds_dwordx4 v192, s[76:77]
	s_add_i32 m0, s92, 0x16000
	ds_read_b128 v[168:171], v216 offset:22528
	ds_read_b128 v[172:175], v216 offset:23552
	global_load_lds_dwordx4 v180, s[76:77]
	s_waitcnt vmcnt(4) lgkmcnt(0)
	s_barrier
	v_mfma_f32_16x16x32_bf16 v[60:63], v[128:131], v[144:147], v[60:63]
	v_mfma_f32_16x16x32_bf16 v[52:55], v[136:139], v[144:147], v[52:55]
	v_mfma_f32_16x16x32_bf16 v[44:47], v[128:131], v[152:155], v[44:47]
	v_mfma_f32_16x16x32_bf16 v[36:39], v[136:139], v[152:155], v[36:39]
	v_mfma_f32_16x16x32_bf16 v[28:31], v[128:131], v[160:163], v[28:31]
	v_mfma_f32_16x16x32_bf16 v[20:23], v[136:139], v[160:163], v[20:23]
	v_mfma_f32_16x16x32_bf16 v[12:15], v[128:131], v[168:171], v[12:15]
	v_mfma_f32_16x16x32_bf16 v[4:7], v[136:139], v[168:171], v[4:7]
	v_mfma_f32_16x16x32_bf16 v[60:63], v[132:135], v[148:151], v[60:63]
	v_mfma_f32_16x16x32_bf16 v[52:55], v[140:143], v[148:151], v[52:55]
	v_mfma_f32_16x16x32_bf16 v[44:47], v[132:135], v[156:159], v[44:47]
	v_mfma_f32_16x16x32_bf16 v[36:39], v[140:143], v[156:159], v[36:39]
	v_mfma_f32_16x16x32_bf16 v[28:31], v[132:135], v[164:167], v[28:31]
	v_mfma_f32_16x16x32_bf16 v[20:23], v[140:143], v[164:167], v[20:23]
	v_mfma_f32_16x16x32_bf16 v[12:15], v[132:135], v[172:175], v[12:15]
	v_mfma_f32_16x16x32_bf16 v[4:7], v[140:143], v[172:175], v[4:7]
	v_mfma_f32_16x16x32_bf16 v[56:59], v[188:191], v[144:147], v[56:59]
	v_mfma_f32_16x16x32_bf16 v[48:51], v[200:203], v[144:147], v[48:51]
	v_mfma_f32_16x16x32_bf16 v[40:43], v[188:191], v[152:155], v[40:43]
	v_mfma_f32_16x16x32_bf16 v[32:35], v[200:203], v[152:155], v[32:35]
	v_mfma_f32_16x16x32_bf16 v[24:27], v[188:191], v[160:163], v[24:27]
	v_mfma_f32_16x16x32_bf16 v[16:19], v[200:203], v[160:163], v[16:19]
	v_mfma_f32_16x16x32_bf16 v[8:11], v[188:191], v[168:171], v[8:11]
	v_mfma_f32_16x16x32_bf16 v[0:3], v[200:203], v[168:171], v[0:3]
	v_mfma_f32_16x16x32_bf16 v[56:59], v[196:199], v[148:151], v[56:59]
	v_mfma_f32_16x16x32_bf16 v[48:51], v[218:221], v[148:151], v[48:51]
	v_mfma_f32_16x16x32_bf16 v[40:43], v[196:199], v[156:159], v[40:43]
	v_mfma_f32_16x16x32_bf16 v[32:35], v[218:221], v[156:159], v[32:35]
	v_mfma_f32_16x16x32_bf16 v[24:27], v[196:199], v[164:167], v[24:27]
	v_mfma_f32_16x16x32_bf16 v[16:19], v[218:221], v[164:167], v[16:19]
	v_mfma_f32_16x16x32_bf16 v[8:11], v[196:199], v[172:175], v[8:11]
	v_mfma_f32_16x16x32_bf16 v[0:3], v[218:221], v[172:175], v[0:3]
	s_barrier
; #define PG8_STAGE(bufoff, gbase, voff) do { _Pragma("unroll") for (int _i = 0; _i < 2; ++_i) \
;         __builtin_amdgcn_global_load_lds((const unsigned*)((const char*)(gbase) + (voff)[_i]), (LAS unsigned*)(lds + (bufoff) + ldsw + _i * 8192), 16, 0, 0); } while (0)
; #define PG8_WAIT_V(n) asm volatile("s_waitcnt vmcnt(" #n ")" ::: "memory")
; template <class Prog>
; __device__ __forceinline__ void gemm_phase(LAS unsigned char* lds, const int K, const Prog& S) {
;     ...
;         for (int t = 0; t < nt; t += 2) {
;             const bool last = (t == nt - 2);
;             const char* a1 = cA + (size_t)(t + 1) * kstep;
;             const char* a2 = last ? nA : cA + (size_t)(t + 2) * kstep; const char* b2 = last ? nB : cB + (size_t)(t + 2) * kstep;
;             const char* a3 = a2 + kstep; const char* b3 = b2 + kstep;
;             PG8_LDB(B0, 0, 0); PG8_SCHED; PG8_LDA(At, 0, 0); PG8_STAGE(PG8_SA(1, 1), a1 + hstep, voffA);
;             PG8_WAIT_L(8); PG8_BAR; PG8_WAIT_L(0); PG8_MMA(0, 0, At, B0); PG8_BAR; PG8_SCHED;
;             PG8_LDB(B1, 0, 1); PG8_STAGE(PG8_SB(0, 0), b2, voffB);
;             PG8_BAR; PG8_WAIT_L(0); PG8_MMA(0, 1, At, B1); PG8_BAR;
;             PG8_LDA(At, 0, 1); PG8_STAGE(PG8_SA(0, 0), a2, voffA);
;             PG8_BAR; PG8_WAIT_L(0); PG8_MMA(1, 0, At, B0); PG8_BAR; PG8_SCHED;
;             PG8_STAGE(PG8_SB(0, 1), b2 + hstep, voffB);
;             PG8_WAIT_V(6); PG8_BAR; PG8_MMA(1, 1, At, B1); PG8_BAR;
;             PG8_LDB(B0, 1, 0); PG8_SCHED; PG8_LDA(At, 1, 0); PG8_STAGE(PG8_SA(0, 1), a2 + hstep, voffA);
;             PG8_WAIT_L(8); PG8_BAR; PG8_WAIT_L(0); PG8_MMA(0, 0, At, B0); PG8_BAR; PG8_SCHED;
;             PG8_LDB(B1, 1, 1); PG8_STAGE(PG8_SB(1, 0), b3, voffB);
;             PG8_BAR; PG8_WAIT_L(0); PG8_MMA(0, 1, At, B1); PG8_BAR;
;             PG8_LDA(At, 1, 1); PG8_STAGE(PG8_SA(1, 0), a3, voffA);
;             PG8_BAR; PG8_WAIT_L(0); PG8_MMA(1, 0, At, B0); PG8_BAR; PG8_SCHED;
;             PG8_STAGE(PG8_SB(1, 1), b3 + hstep, voffB);
;             PG8_WAIT_V(6); PG8_BAR; PG8_MMA(1, 1, At, B1); PG8_BAR;
;     __device__ __forceinline__ void epi(f32x4 (&acc)[2][2][4][2], const pg8::Unit& u, int wr, int wc, int fr, int fq) const {
;     ...
;         const int pn = u.pn;
;         const int mode = (pn < 8) ? 1 : ((pn >= 12 && pn < 16) || (pn >= 20 && pn < 24) || (pn >= 30 && pn < 34)) ? 2 : (pn >= 34 ? 3 : 0);
	s_add_u32 s98, s46, 0x80000
	s_addc_u32 s99, s47, 0
	ds_read_b128 v[128:131], v244 offset:32768
	ds_read_b128 v[132:135], v244 offset:33792
	ds_read_b128 v[136:139], v244 offset:34816
	ds_read_b128 v[140:143], v244 offset:35840
	s_mov_b32 m0, s92
	ds_read_b128 v[188:191], v244 offset:49152
	ds_read_b128 v[196:199], v244 offset:50176
	ds_read_b128 v[200:203], v244 offset:51200
	ds_read_b128 v[218:221], v244 offset:52224
	global_load_lds_dwordx4 v176, s[46:47]
	s_add_i32 m0, s92, 0x2000
	ds_read_b128 v[144:147], v216 offset:32768
	ds_read_b128 v[148:151], v216 offset:33792
	ds_read_b128 v[152:155], v216 offset:34816
	ds_read_b128 v[156:159], v216 offset:35840
	global_load_lds_dwordx4 v178, s[46:47]
	s_add_i32 m0, s92, 0x4000
	ds_read_b128 v[160:163], v216 offset:36864
	ds_read_b128 v[164:167], v216 offset:37888
	ds_read_b128 v[168:171], v216 offset:38912
	global_load_lds_dwordx4 v176, s[98:99]
	s_add_i32 m0, s92, 0x6000
	ds_read_b128 v[172:175], v216 offset:39936
	global_load_lds_dwordx4 v178, s[98:99]
	s_waitcnt lgkmcnt(0)
	s_barrier
	v_mfma_f32_16x16x32_bf16 v[124:127], v[128:131], v[144:147], v[124:127]
	v_mfma_f32_16x16x32_bf16 v[116:119], v[136:139], v[144:147], v[116:119]
	v_mfma_f32_16x16x32_bf16 v[108:111], v[128:131], v[152:155], v[108:111]
	v_mfma_f32_16x16x32_bf16 v[100:103], v[136:139], v[152:155], v[100:103]
	v_mfma_f32_16x16x32_bf16 v[92:95], v[128:131], v[160:163], v[92:95]
	v_mfma_f32_16x16x32_bf16 v[84:87], v[136:139], v[160:163], v[84:87]
	v_mfma_f32_16x16x32_bf16 v[76:79], v[128:131], v[168:171], v[76:79]
	v_mfma_f32_16x16x32_bf16 v[68:71], v[136:139], v[168:171], v[68:71]
	v_mfma_f32_16x16x32_bf16 v[124:127], v[132:135], v[148:151], v[124:127]
	v_mfma_f32_16x16x32_bf16 v[116:119], v[140:143], v[148:151], v[116:119]
	v_mfma_f32_16x16x32_bf16 v[108:111], v[132:135], v[156:159], v[108:111]
	v_mfma_f32_16x16x32_bf16 v[100:103], v[140:143], v[156:159], v[100:103]
	v_mfma_f32_16x16x32_bf16 v[92:95], v[132:135], v[164:167], v[92:95]
	v_mfma_f32_16x16x32_bf16 v[84:87], v[140:143], v[164:167], v[84:87]
	v_mfma_f32_16x16x32_bf16 v[76:79], v[132:135], v[172:175], v[76:79]
	v_mfma_f32_16x16x32_bf16 v[68:71], v[140:143], v[172:175], v[68:71]
	v_mfma_f32_16x16x32_bf16 v[120:123], v[188:191], v[144:147], v[120:123]
	v_mfma_f32_16x16x32_bf16 v[112:115], v[200:203], v[144:147], v[112:115]
	v_mfma_f32_16x16x32_bf16 v[104:107], v[188:191], v[152:155], v[104:107]
	v_mfma_f32_16x16x32_bf16 v[96:99], v[200:203], v[152:155], v[96:99]
	v_mfma_f32_16x16x32_bf16 v[88:91], v[188:191], v[160:163], v[88:91]
	v_mfma_f32_16x16x32_bf16 v[80:83], v[200:203], v[160:163], v[80:83]
	v_mfma_f32_16x16x32_bf16 v[72:75], v[188:191], v[168:171], v[72:75]
	v_mfma_f32_16x16x32_bf16 v[64:67], v[200:203], v[168:171], v[64:67]
	v_mfma_f32_16x16x32_bf16 v[120:123], v[196:199], v[148:151], v[120:123]
	v_mfma_f32_16x16x32_bf16 v[112:115], v[218:221], v[148:151], v[112:115]
	v_mfma_f32_16x16x32_bf16 v[104:107], v[196:199], v[156:159], v[104:107]
	v_mfma_f32_16x16x32_bf16 v[96:99], v[218:221], v[156:159], v[96:99]
	v_mfma_f32_16x16x32_bf16 v[88:91], v[196:199], v[164:167], v[88:91]
	v_mfma_f32_16x16x32_bf16 v[80:83], v[218:221], v[164:167], v[80:83]
	v_mfma_f32_16x16x32_bf16 v[72:75], v[196:199], v[172:175], v[72:75]
	v_mfma_f32_16x16x32_bf16 v[64:67], v[218:221], v[172:175], v[64:67]
	s_barrier
	s_add_u32 s98, s44, 0x80
	s_addc_u32 s99, s45, 0
	s_add_i32 m0, s92, 0x18000
	ds_read_b128 v[144:147], v216 offset:49152
	ds_read_b128 v[148:151], v216 offset:50176
	global_load_lds_dwordx4 v192, s[98:99]
	s_add_i32 m0, s92, 0x1a000
	ds_read_b128 v[152:155], v216 offset:51200
	ds_read_b128 v[156:159], v216 offset:52224
	global_load_lds_dwordx4 v180, s[98:99]
	s_add_i32 m0, s92, 0x1c000
	s_add_u32 s76, s44, 0x80080
	s_addc_u32 s77, s45, 0
	ds_read_b128 v[160:163], v216 offset:53248
	ds_read_b128 v[164:167], v216 offset:54272
	global_load_lds_dwordx4 v192, s[76:77]
	s_add_i32 m0, s92, 0x1e000
	ds_read_b128 v[168:171], v216 offset:55296
	ds_read_b128 v[172:175], v216 offset:56320
	global_load_lds_dwordx4 v180, s[76:77]
	s_waitcnt vmcnt(4) lgkmcnt(0)
	s_barrier
	v_mfma_f32_16x16x32_bf16 v[60:63], v[128:131], v[144:147], v[60:63]
	v_mfma_f32_16x16x32_bf16 v[52:55], v[136:139], v[144:147], v[52:55]
	v_mfma_f32_16x16x32_bf16 v[44:47], v[128:131], v[152:155], v[44:47]
	v_mfma_f32_16x16x32_bf16 v[36:39], v[136:139], v[152:155], v[36:39]
	v_mfma_f32_16x16x32_bf16 v[28:31], v[128:131], v[160:163], v[28:31]
	v_mfma_f32_16x16x32_bf16 v[20:23], v[136:139], v[160:163], v[20:23]
	v_mfma_f32_16x16x32_bf16 v[12:15], v[128:131], v[168:171], v[12:15]
	v_mfma_f32_16x16x32_bf16 v[4:7], v[136:139], v[168:171], v[4:7]
	v_mfma_f32_16x16x32_bf16 v[60:63], v[132:135], v[148:151], v[60:63]
	v_mfma_f32_16x16x32_bf16 v[52:55], v[140:143], v[148:151], v[52:55]
	v_mfma_f32_16x16x32_bf16 v[44:47], v[132:135], v[156:159], v[44:47]
	v_mfma_f32_16x16x32_bf16 v[36:39], v[140:143], v[156:159], v[36:39]
	v_mfma_f32_16x16x32_bf16 v[28:31], v[132:135], v[164:167], v[28:31]
	v_mfma_f32_16x16x32_bf16 v[20:23], v[140:143], v[164:167], v[20:23]
	v_mfma_f32_16x16x32_bf16 v[12:15], v[132:135], v[172:175], v[12:15]
	v_mfma_f32_16x16x32_bf16 v[4:7], v[140:143], v[172:175], v[4:7]
	v_mfma_f32_16x16x32_bf16 v[56:59], v[188:191], v[144:147], v[56:59]
	v_mfma_f32_16x16x32_bf16 v[48:51], v[200:203], v[144:147], v[48:51]
	v_mfma_f32_16x16x32_bf16 v[40:43], v[188:191], v[152:155], v[40:43]
	v_mfma_f32_16x16x32_bf16 v[32:35], v[200:203], v[152:155], v[32:35]
	v_mfma_f32_16x16x32_bf16 v[24:27], v[188:191], v[160:163], v[24:27]
	v_mfma_f32_16x16x32_bf16 v[16:19], v[200:203], v[160:163], v[16:19]
	v_mfma_f32_16x16x32_bf16 v[8:11], v[188:191], v[168:171], v[8:11]
	v_mfma_f32_16x16x32_bf16 v[0:3], v[200:203], v[168:171], v[0:3]
	v_mfma_f32_16x16x32_bf16 v[56:59], v[196:199], v[148:151], v[56:59]
	v_mfma_f32_16x16x32_bf16 v[48:51], v[218:221], v[148:151], v[48:51]
	v_mfma_f32_16x16x32_bf16 v[40:43], v[196:199], v[156:159], v[40:43]
	v_mfma_f32_16x16x32_bf16 v[32:35], v[218:221], v[156:159], v[32:35]
	v_mfma_f32_16x16x32_bf16 v[24:27], v[196:199], v[164:167], v[24:27]
	v_mfma_f32_16x16x32_bf16 v[16:19], v[218:221], v[164:167], v[16:19]
	v_mfma_f32_16x16x32_bf16 v[8:11], v[196:199], v[172:175], v[8:11]
	v_mfma_f32_16x16x32_bf16 v[0:3], v[218:221], v[172:175], v[0:3]
	s_add_i32 s69, s69, 2
	s_add_u32 s40, s40, 0x100
	s_addc_u32 s41, s41, 0
	s_add_u32 s9, s9, 0x100
	s_addc_u32 s15, s15, 0
	s_cmp_gt_u32 s69, 29
	s_barrier
	s_cbranch_scc0 .LBB0_101
	s_cmp_lt_i32 s75, 8
	s_mov_b32 s9, 1
	s_cbranch_scc1 .LBB0_110
	s_sub_i32 s4, s75, 30
	s_cmp_lt_u32 s4, 4
	s_mov_b32 s9, 2
	s_cbranch_scc1 .LBB0_110
	s_and_b32 s9, s75, 0x7ffffffc
	s_cmp_lt_i32 s9, 20
	s_cbranch_scc1 .LBB0_106
	s_cmp_lg_u32 s9, 20
	s_cselect_b64 s[4:5], -1, 0
	s_cbranch_execz .LBB0_107
	s_branch .LBB0_108

; #define PG8_STAGE(bufoff, gbase, voff) do { _Pragma("unroll") for (int _i = 0; _i < 2; ++_i) \
;         __builtin_amdgcn_global_load_lds((const unsigned*)((const char*)(gbase) + (voff)[_i]), (LAS unsigned*)(lds + (bufoff) + ldsw + _i * 8192), 16, 0, 0); } while (0)
; #define PG8_LDA(dst, b, h) do { _Pragma("unroll") for (int m = 0; m < 4; ++m) _Pragma("unroll") for (int k = 0; k < 2; ++k) dst[m][k] = *(const LAS bf16x8*)(lds + PG8_SA(b, h) + aoff + m * 2048 + k * 1024); } while (0)
; #define PG8_WAIT_V(n) asm volatile("s_waitcnt vmcnt(" #n ")" ::: "memory")
; #define PG8_WAIT_L(n) asm volatile("s_waitcnt lgkmcnt(" #n ")" ::: "memory")
; template <class Prog>
; __device__ __forceinline__ void gemm_phase(LAS unsigned char* lds, const int K, const Prog& S) {
;     ...
;         for (int t = 0; t < nt; t += 2) {
;             const bool last = (t == nt - 2);
;             const char* a1 = cA + (size_t)(t + 1) * kstep;
;             const char* a2 = last ? nA : cA + (size_t)(t + 2) * kstep; const char* b2 = last ? nB : cB + (size_t)(t + 2) * kstep;
;             const char* a3 = a2 + kstep; const char* b3 = b2 + kstep;
;             PG8_LDB(B0, 0, 0); PG8_SCHED; PG8_LDA(At, 0, 0); PG8_STAGE(PG8_SA(1, 1), a1 + hstep, voffA);
;             PG8_WAIT_L(8); PG8_BAR; PG8_WAIT_L(0); PG8_MMA(0, 0, At, B0); PG8_BAR; PG8_SCHED;
;             PG8_LDB(B1, 0, 1); PG8_STAGE(PG8_SB(0, 0), b2, voffB);
;             PG8_BAR; PG8_WAIT_L(0); PG8_MMA(0, 1, At, B1); PG8_BAR;
;             PG8_LDA(At, 0, 1); PG8_STAGE(PG8_SA(0, 0), a2, voffA);
;             PG8_BAR; PG8_WAIT_L(0); PG8_MMA(1, 0, At, B0); PG8_BAR; PG8_SCHED;
;             PG8_STAGE(PG8_SB(0, 1), b2 + hstep, voffB);
;             PG8_WAIT_V(6); PG8_BAR; PG8_MMA(1, 1, At, B1); PG8_BAR;
;             PG8_LDB(B0, 1, 0); PG8_SCHED; PG8_LDA(At, 1, 0); PG8_STAGE(PG8_SA(0, 1), a2 + hstep, voffA);
;             PG8_WAIT_L(8); PG8_BAR; PG8_WAIT_L(0); PG8_MMA(0, 0, At, B0); PG8_BAR; PG8_SCHED;
;             PG8_LDB(B1, 1, 1); PG8_STAGE(PG8_SB(1, 0), b3, voffB);
;             PG8_BAR; PG8_WAIT_L(0); PG8_MMA(0, 1, At, B1); PG8_BAR;
;             PG8_LDA(At, 1, 1); PG8_STAGE(PG8_SA(1, 0), a3, voffA);
;             PG8_BAR; PG8_WAIT_L(0); PG8_MMA(1, 0, At, B0); PG8_BAR; PG8_SCHED;
;             PG8_STAGE(PG8_SB(1, 1), b3 + hstep, voffB);
;             PG8_WAIT_V(6); PG8_BAR; PG8_MMA(1, 1, At, B1); PG8_BAR;
.LBB0_400:
	s_add_u32 s46, s44, 0xfffc0080
	s_addc_u32 s47, s45, -1
	s_cmp_eq_u32 s55, 12
	s_cselect_b32 s53, s7, s47
	s_cselect_b32 s52, s6, s46
	s_cselect_b32 s47, s9, s43
	s_cselect_b32 s46, s8, s41
	s_add_u32 s84, s44, 0xfffc0000
	s_addc_u32 s85, s45, -1
	ds_read_b128 v[128:131], v206
	ds_read_b128 v[132:135], v206 offset:1024
	ds_read_b128 v[136:139], v206 offset:2048
	ds_read_b128 v[140:143], v206 offset:3072
	s_add_i32 m0, s74, 0x8000
	ds_read_b128 v[176:179], v206 offset:16384
	ds_read_b128 v[180:183], v206 offset:17408
	ds_read_b128 v[184:187], v206 offset:18432
	ds_read_b128 v[188:191], v206 offset:19456
	global_load_lds_dwordx4 v202, s[84:85]
	s_add_i32 m0, s74, 0xa000
	ds_read_b128 v[144:147], v247
	ds_read_b128 v[148:151], v247 offset:1024
	ds_read_b128 v[152:155], v247 offset:2048
	ds_read_b128 v[156:159], v247 offset:3072
	global_load_lds_dwordx4 v204, s[84:85]
	s_add_i32 m0, s74, 0xc000
	ds_read_b128 v[160:163], v247 offset:4096
	ds_read_b128 v[164:167], v247 offset:5120
	ds_read_b128 v[168:171], v247 offset:6144
	global_load_lds_dwordx4 v202, s[44:45]
	s_add_i32 m0, s74, 0xe000
	ds_read_b128 v[172:175], v247 offset:7168
	global_load_lds_dwordx4 v204, s[44:45]
	s_waitcnt lgkmcnt(0)
	s_barrier
	v_mfma_f32_16x16x32_bf16 v[124:127], v[128:131], v[144:147], v[124:127]
	v_mfma_f32_16x16x32_bf16 v[120:123], v[136:139], v[144:147], v[120:123]
	v_mfma_f32_16x16x32_bf16 v[116:119], v[128:131], v[152:155], v[116:119]
	v_mfma_f32_16x16x32_bf16 v[112:115], v[136:139], v[152:155], v[112:115]
	v_mfma_f32_16x16x32_bf16 v[108:111], v[128:131], v[160:163], v[108:111]
	v_mfma_f32_16x16x32_bf16 v[104:107], v[136:139], v[160:163], v[104:107]
	v_mfma_f32_16x16x32_bf16 v[100:103], v[128:131], v[168:171], v[100:103]
	v_mfma_f32_16x16x32_bf16 v[96:99], v[136:139], v[168:171], v[96:99]
	v_mfma_f32_16x16x32_bf16 v[124:127], v[132:135], v[148:151], v[124:127]
	v_mfma_f32_16x16x32_bf16 v[120:123], v[140:143], v[148:151], v[120:123]
	v_mfma_f32_16x16x32_bf16 v[116:119], v[132:135], v[156:159], v[116:119]
	v_mfma_f32_16x16x32_bf16 v[112:115], v[140:143], v[156:159], v[112:115]
	v_mfma_f32_16x16x32_bf16 v[108:111], v[132:135], v[164:167], v[108:111]
	v_mfma_f32_16x16x32_bf16 v[104:107], v[140:143], v[164:167], v[104:107]
	v_mfma_f32_16x16x32_bf16 v[100:103], v[132:135], v[172:175], v[100:103]
	v_mfma_f32_16x16x32_bf16 v[96:99], v[140:143], v[172:175], v[96:99]
	v_mfma_f32_16x16x32_bf16 v[92:95], v[176:179], v[144:147], v[92:95]
	v_mfma_f32_16x16x32_bf16 v[88:91], v[184:187], v[144:147], v[88:91]
	v_mfma_f32_16x16x32_bf16 v[84:87], v[176:179], v[152:155], v[84:87]
	v_mfma_f32_16x16x32_bf16 v[80:83], v[184:187], v[152:155], v[80:83]
	v_mfma_f32_16x16x32_bf16 v[76:79], v[176:179], v[160:163], v[76:79]
	v_mfma_f32_16x16x32_bf16 v[72:75], v[184:187], v[160:163], v[72:75]
	v_mfma_f32_16x16x32_bf16 v[68:71], v[176:179], v[168:171], v[68:71]
	v_mfma_f32_16x16x32_bf16 v[64:67], v[184:187], v[168:171], v[64:67]
	v_mfma_f32_16x16x32_bf16 v[92:95], v[180:183], v[148:151], v[92:95]
	v_mfma_f32_16x16x32_bf16 v[88:91], v[188:191], v[148:151], v[88:91]
	v_mfma_f32_16x16x32_bf16 v[84:87], v[180:183], v[156:159], v[84:87]
	v_mfma_f32_16x16x32_bf16 v[80:83], v[188:191], v[156:159], v[80:83]
	v_mfma_f32_16x16x32_bf16 v[76:79], v[180:183], v[164:167], v[76:79]
	v_mfma_f32_16x16x32_bf16 v[72:75], v[188:191], v[164:167], v[72:75]
	v_mfma_f32_16x16x32_bf16 v[68:71], v[180:183], v[172:175], v[68:71]
	v_mfma_f32_16x16x32_bf16 v[64:67], v[188:191], v[172:175], v[64:67]
	s_barrier
	s_add_i32 m0, s74, 0x10000
	ds_read_b128 v[144:147], v247 offset:16384
	ds_read_b128 v[148:151], v247 offset:17408
	global_load_lds_dwordx4 v192, s[46:47]
	s_add_i32 m0, s74, 0x12000
	ds_read_b128 v[152:155], v247 offset:18432
	ds_read_b128 v[156:159], v247 offset:19456
	global_load_lds_dwordx4 v200, s[46:47]
	s_add_i32 m0, s74, 0x14000
	s_add_u32 s84, s46, 0x40000
	s_addc_u32 s85, s47, 0
	ds_read_b128 v[160:163], v247 offset:20480
	ds_read_b128 v[164:167], v247 offset:21504
	global_load_lds_dwordx4 v192, s[84:85]
	s_add_i32 m0, s74, 0x16000
	ds_read_b128 v[168:171], v247 offset:22528
	ds_read_b128 v[172:175], v247 offset:23552
	global_load_lds_dwordx4 v200, s[84:85]
	s_waitcnt vmcnt(4) lgkmcnt(0)
	s_barrier
	v_mfma_f32_16x16x32_bf16 v[60:63], v[128:131], v[144:147], v[60:63]
	v_mfma_f32_16x16x32_bf16 v[56:59], v[136:139], v[144:147], v[56:59]
	v_mfma_f32_16x16x32_bf16 v[52:55], v[128:131], v[152:155], v[52:55]
	v_mfma_f32_16x16x32_bf16 v[48:51], v[136:139], v[152:155], v[48:51]
	v_mfma_f32_16x16x32_bf16 v[44:47], v[128:131], v[160:163], v[44:47]
	v_mfma_f32_16x16x32_bf16 v[40:43], v[136:139], v[160:163], v[40:43]
	v_mfma_f32_16x16x32_bf16 v[36:39], v[128:131], v[168:171], v[36:39]
	v_mfma_f32_16x16x32_bf16 v[32:35], v[136:139], v[168:171], v[32:35]
	v_mfma_f32_16x16x32_bf16 v[60:63], v[132:135], v[148:151], v[60:63]
	v_mfma_f32_16x16x32_bf16 v[56:59], v[140:143], v[148:151], v[56:59]
	v_mfma_f32_16x16x32_bf16 v[52:55], v[132:135], v[156:159], v[52:55]
	v_mfma_f32_16x16x32_bf16 v[48:51], v[140:143], v[156:159], v[48:51]
	v_mfma_f32_16x16x32_bf16 v[44:47], v[132:135], v[164:167], v[44:47]
	v_mfma_f32_16x16x32_bf16 v[40:43], v[140:143], v[164:167], v[40:43]
	v_mfma_f32_16x16x32_bf16 v[36:39], v[132:135], v[172:175], v[36:39]
	v_mfma_f32_16x16x32_bf16 v[32:35], v[140:143], v[172:175], v[32:35]
	v_mfma_f32_16x16x32_bf16 v[28:31], v[176:179], v[144:147], v[28:31]
	v_mfma_f32_16x16x32_bf16 v[24:27], v[184:187], v[144:147], v[24:27]
	v_mfma_f32_16x16x32_bf16 v[20:23], v[176:179], v[152:155], v[20:23]
	v_mfma_f32_16x16x32_bf16 v[16:19], v[184:187], v[152:155], v[16:19]
	v_mfma_f32_16x16x32_bf16 v[12:15], v[176:179], v[160:163], v[12:15]
	v_mfma_f32_16x16x32_bf16 v[8:11], v[184:187], v[160:163], v[8:11]
	v_mfma_f32_16x16x32_bf16 v[4:7], v[176:179], v[168:171], v[4:7]
	v_mfma_f32_16x16x32_bf16 v[0:3], v[184:187], v[168:171], v[0:3]
	v_mfma_f32_16x16x32_bf16 v[28:31], v[180:183], v[148:151], v[28:31]
	v_mfma_f32_16x16x32_bf16 v[24:27], v[188:191], v[148:151], v[24:27]
	v_mfma_f32_16x16x32_bf16 v[20:23], v[180:183], v[156:159], v[20:23]
	v_mfma_f32_16x16x32_bf16 v[16:19], v[188:191], v[156:159], v[16:19]
	v_mfma_f32_16x16x32_bf16 v[12:15], v[180:183], v[164:167], v[12:15]
	v_mfma_f32_16x16x32_bf16 v[8:11], v[188:191], v[164:167], v[8:11]
	v_mfma_f32_16x16x32_bf16 v[4:7], v[180:183], v[172:175], v[4:7]
	v_mfma_f32_16x16x32_bf16 v[0:3], v[188:191], v[172:175], v[0:3]
	s_barrier
; #define PG8_STAGE(bufoff, gbase, voff) do { _Pragma("unroll") for (int _i = 0; _i < 2; ++_i) \
;         __builtin_amdgcn_global_load_lds((const unsigned*)((const char*)(gbase) + (voff)[_i]), (LAS unsigned*)(lds + (bufoff) + ldsw + _i * 8192), 16, 0, 0); } while (0)
; #define PG8_LDA(dst, b, h) do { _Pragma("unroll") for (int m = 0; m < 4; ++m) _Pragma("unroll") for (int k = 0; k < 2; ++k) dst[m][k] = *(const LAS bf16x8*)(lds + PG8_SA(b, h) + aoff + m * 2048 + k * 1024); } while (0)
; #define PG8_WAIT_V(n) asm volatile("s_waitcnt vmcnt(" #n ")" ::: "memory")
; #define PG8_WAIT_L(n) asm volatile("s_waitcnt lgkmcnt(" #n ")" ::: "memory")
; template <class Prog>
; __device__ __forceinline__ void gemm_phase(LAS unsigned char* lds, const int K, const Prog& S) {
;     ...
;         for (int t = 0; t < nt; t += 2) {
;             const bool last = (t == nt - 2);
;             const char* a1 = cA + (size_t)(t + 1) * kstep;
;             const char* a2 = last ? nA : cA + (size_t)(t + 2) * kstep; const char* b2 = last ? nB : cB + (size_t)(t + 2) * kstep;
;             const char* a3 = a2 + kstep; const char* b3 = b2 + kstep;
;             PG8_LDB(B0, 0, 0); PG8_SCHED; PG8_LDA(At, 0, 0); PG8_STAGE(PG8_SA(1, 1), a1 + hstep, voffA);
;             PG8_WAIT_L(8); PG8_BAR; PG8_WAIT_L(0); PG8_MMA(0, 0, At, B0); PG8_BAR; PG8_SCHED;
;             PG8_LDB(B1, 0, 1); PG8_STAGE(PG8_SB(0, 0), b2, voffB);
;             PG8_BAR; PG8_WAIT_L(0); PG8_MMA(0, 1, At, B1); PG8_BAR;
;             PG8_LDA(At, 0, 1); PG8_STAGE(PG8_SA(0, 0), a2, voffA);
;             PG8_BAR; PG8_WAIT_L(0); PG8_MMA(1, 0, At, B0); PG8_BAR; PG8_SCHED;
;             PG8_STAGE(PG8_SB(0, 1), b2 + hstep, voffB);
;             PG8_WAIT_V(6); PG8_BAR; PG8_MMA(1, 1, At, B1); PG8_BAR;
;             PG8_LDB(B0, 1, 0); PG8_SCHED; PG8_LDA(At, 1, 0); PG8_STAGE(PG8_SA(0, 1), a2 + hstep, voffA);
;             PG8_WAIT_L(8); PG8_BAR; PG8_WAIT_L(0); PG8_MMA(0, 0, At, B0); PG8_BAR; PG8_SCHED;
;             PG8_LDB(B1, 1, 1); PG8_STAGE(PG8_SB(1, 0), b3, voffB);
;             PG8_BAR; PG8_WAIT_L(0); PG8_MMA(0, 1, At, B1); PG8_BAR;
;             PG8_LDA(At, 1, 1); PG8_STAGE(PG8_SA(1, 0), a3, voffA);
;             PG8_BAR; PG8_WAIT_L(0); PG8_MMA(1, 0, At, B0); PG8_BAR; PG8_SCHED;
;             PG8_STAGE(PG8_SB(1, 1), b3 + hstep, voffB);
;             PG8_WAIT_V(6); PG8_BAR; PG8_MMA(1, 1, At, B1); PG8_BAR;
	s_add_u32 s98, s52, 0x40000
	s_addc_u32 s99, s53, 0
	ds_read_b128 v[128:131], v206 offset:32768
	ds_read_b128 v[132:135], v206 offset:33792
	ds_read_b128 v[136:139], v206 offset:34816
	ds_read_b128 v[140:143], v206 offset:35840
	s_mov_b32 m0, s74
	ds_read_b128 v[176:179], v206 offset:49152
	ds_read_b128 v[180:183], v206 offset:50176
	ds_read_b128 v[184:187], v206 offset:51200
	ds_read_b128 v[188:191], v206 offset:52224
	global_load_lds_dwordx4 v196, s[52:53]
	s_add_i32 m0, s74, 0x2000
	ds_read_b128 v[144:147], v247 offset:32768
	ds_read_b128 v[148:151], v247 offset:33792
	ds_read_b128 v[152:155], v247 offset:34816
	ds_read_b128 v[156:159], v247 offset:35840
	global_load_lds_dwordx4 v198, s[52:53]
	s_add_i32 m0, s74, 0x4000
	ds_read_b128 v[160:163], v247 offset:36864
	ds_read_b128 v[164:167], v247 offset:37888
	ds_read_b128 v[168:171], v247 offset:38912
	global_load_lds_dwordx4 v196, s[98:99]
	s_add_i32 m0, s74, 0x6000
	ds_read_b128 v[172:175], v247 offset:39936
	global_load_lds_dwordx4 v198, s[98:99]
	s_waitcnt lgkmcnt(0)
	s_barrier
	v_mfma_f32_16x16x32_bf16 v[124:127], v[128:131], v[144:147], v[124:127]
	v_mfma_f32_16x16x32_bf16 v[120:123], v[136:139], v[144:147], v[120:123]
	v_mfma_f32_16x16x32_bf16 v[116:119], v[128:131], v[152:155], v[116:119]
	v_mfma_f32_16x16x32_bf16 v[112:115], v[136:139], v[152:155], v[112:115]
	v_mfma_f32_16x16x32_bf16 v[108:111], v[128:131], v[160:163], v[108:111]
	v_mfma_f32_16x16x32_bf16 v[104:107], v[136:139], v[160:163], v[104:107]
	v_mfma_f32_16x16x32_bf16 v[100:103], v[128:131], v[168:171], v[100:103]
	v_mfma_f32_16x16x32_bf16 v[96:99], v[136:139], v[168:171], v[96:99]
	v_mfma_f32_16x16x32_bf16 v[124:127], v[132:135], v[148:151], v[124:127]
	v_mfma_f32_16x16x32_bf16 v[120:123], v[140:143], v[148:151], v[120:123]
	v_mfma_f32_16x16x32_bf16 v[116:119], v[132:135], v[156:159], v[116:119]
	v_mfma_f32_16x16x32_bf16 v[112:115], v[140:143], v[156:159], v[112:115]
	v_mfma_f32_16x16x32_bf16 v[108:111], v[132:135], v[164:167], v[108:111]
	v_mfma_f32_16x16x32_bf16 v[104:107], v[140:143], v[164:167], v[104:107]
	v_mfma_f32_16x16x32_bf16 v[100:103], v[132:135], v[172:175], v[100:103]
	v_mfma_f32_16x16x32_bf16 v[96:99], v[140:143], v[172:175], v[96:99]
	v_mfma_f32_16x16x32_bf16 v[92:95], v[176:179], v[144:147], v[92:95]
	v_mfma_f32_16x16x32_bf16 v[88:91], v[184:187], v[144:147], v[88:91]
	v_mfma_f32_16x16x32_bf16 v[84:87], v[176:179], v[152:155], v[84:87]
	v_mfma_f32_16x16x32_bf16 v[80:83], v[184:187], v[152:155], v[80:83]
	v_mfma_f32_16x16x32_bf16 v[76:79], v[176:179], v[160:163], v[76:79]
	v_mfma_f32_16x16x32_bf16 v[72:75], v[184:187], v[160:163], v[72:75]
	v_mfma_f32_16x16x32_bf16 v[68:71], v[176:179], v[168:171], v[68:71]
	v_mfma_f32_16x16x32_bf16 v[64:67], v[184:187], v[168:171], v[64:67]
	v_mfma_f32_16x16x32_bf16 v[92:95], v[180:183], v[148:151], v[92:95]
	v_mfma_f32_16x16x32_bf16 v[88:91], v[188:191], v[148:151], v[88:91]
	v_mfma_f32_16x16x32_bf16 v[84:87], v[180:183], v[156:159], v[84:87]
	v_mfma_f32_16x16x32_bf16 v[80:83], v[188:191], v[156:159], v[80:83]
	v_mfma_f32_16x16x32_bf16 v[76:79], v[180:183], v[164:167], v[76:79]
	v_mfma_f32_16x16x32_bf16 v[72:75], v[188:191], v[164:167], v[72:75]
	v_mfma_f32_16x16x32_bf16 v[68:71], v[180:183], v[172:175], v[68:71]
	v_mfma_f32_16x16x32_bf16 v[64:67], v[188:191], v[172:175], v[64:67]
	s_barrier
; #define PG8_STAGE(bufoff, gbase, voff) do { _Pragma("unroll") for (int _i = 0; _i < 2; ++_i) \
;         __builtin_amdgcn_global_load_lds((const unsigned*)((const char*)(gbase) + (voff)[_i]), (LAS unsigned*)(lds + (bufoff) + ldsw + _i * 8192), 16, 0, 0); } while (0)
; #define PG8_BAR __builtin_amdgcn_s_barrier()
; template <class Prog>
; __device__ __forceinline__ void gemm_phase(LAS unsigned char* lds, const int K, const Prog& S) {
;     ...
;         for (int t = 0; t < nt; t += 2) {
;             const bool last = (t == nt - 2);
;             const char* a1 = cA + (size_t)(t + 1) * kstep;
;             const char* a2 = last ? nA : cA + (size_t)(t + 2) * kstep; const char* b2 = last ? nB : cB + (size_t)(t + 2) * kstep;
;             const char* a3 = a2 + kstep; const char* b3 = b2 + kstep;
;             PG8_LDB(B0, 0, 0); PG8_SCHED; PG8_LDA(At, 0, 0); PG8_STAGE(PG8_SA(1, 1), a1 + hstep, voffA);
;             PG8_WAIT_L(8); PG8_BAR; PG8_WAIT_L(0); PG8_MMA(0, 0, At, B0); PG8_BAR; PG8_SCHED;
;             PG8_LDB(B1, 0, 1); PG8_STAGE(PG8_SB(0, 0), b2, voffB);
;             PG8_BAR; PG8_WAIT_L(0); PG8_MMA(0, 1, At, B1); PG8_BAR;
;             PG8_LDA(At, 0, 1); PG8_STAGE(PG8_SA(0, 0), a2, voffA);
;             PG8_BAR; PG8_WAIT_L(0); PG8_MMA(1, 0, At, B0); PG8_BAR; PG8_SCHED;
;             PG8_STAGE(PG8_SB(0, 1), b2 + hstep, voffB);
;             PG8_WAIT_V(6); PG8_BAR; PG8_MMA(1, 1, At, B1); PG8_BAR;
;             PG8_LDB(B0, 1, 0); PG8_SCHED; PG8_LDA(At, 1, 0); PG8_STAGE(PG8_SA(0, 1), a2 + hstep, voffA);
;             PG8_WAIT_L(8); PG8_BAR; PG8_WAIT_L(0); PG8_MMA(0, 0, At, B0); PG8_BAR; PG8_SCHED;
;             PG8_LDB(B1, 1, 1); PG8_STAGE(PG8_SB(1, 0), b3, voffB);
;             PG8_BAR; PG8_WAIT_L(0); PG8_MMA(0, 1, At, B1); PG8_BAR;
;             PG8_LDA(At, 1, 1); PG8_STAGE(PG8_SA(1, 0), a3, voffA);
;             PG8_BAR; PG8_WAIT_L(0); PG8_MMA(1, 0, At, B0); PG8_BAR; PG8_SCHED;
;             PG8_STAGE(PG8_SB(1, 1), b3 + hstep, voffB);
;             PG8_WAIT_V(6); PG8_BAR; PG8_MMA(1, 1, At, B1); PG8_BAR;
;     __device__ __forceinline__ void epi(f32x4 (&acc)[2][2][4][2], const pg8::Unit& u, int wr, int wc, int fr, int fq) const {
;         const int row0 = u.pm * 256 + wr * 64 + fr, col0 = u.pn * 256 + wc * 32 + 8 * fq;
;         const int sub = u.sub;
;         u32x4 gn[4][2][2], gd[4][2][2];
;         const int dsub = sub < 2 ? sub + 1 : sub;
	s_add_u32 s98, s46, 0x80
	s_addc_u32 s99, s47, 0
	s_add_i32 m0, s74, 0x18000
	ds_read_b128 v[144:147], v247 offset:49152
	ds_read_b128 v[148:151], v247 offset:50176
	global_load_lds_dwordx4 v192, s[98:99]
	s_add_i32 m0, s74, 0x1a000
	ds_read_b128 v[152:155], v247 offset:51200
	ds_read_b128 v[156:159], v247 offset:52224
	global_load_lds_dwordx4 v200, s[98:99]
	s_add_i32 m0, s74, 0x1c000
	s_add_u32 s84, s46, 0x40080
	s_addc_u32 s85, s47, 0
	ds_read_b128 v[160:163], v247 offset:53248
	ds_read_b128 v[164:167], v247 offset:54272
	global_load_lds_dwordx4 v192, s[84:85]
	s_add_i32 m0, s74, 0x1e000
	ds_read_b128 v[168:171], v247 offset:55296
	ds_read_b128 v[172:175], v247 offset:56320
	global_load_lds_dwordx4 v200, s[84:85]
	s_waitcnt vmcnt(4) lgkmcnt(0)
	s_barrier
	v_mfma_f32_16x16x32_bf16 v[60:63], v[128:131], v[144:147], v[60:63]
	v_mfma_f32_16x16x32_bf16 v[56:59], v[136:139], v[144:147], v[56:59]
	v_mfma_f32_16x16x32_bf16 v[52:55], v[128:131], v[152:155], v[52:55]
	v_mfma_f32_16x16x32_bf16 v[48:51], v[136:139], v[152:155], v[48:51]
	v_mfma_f32_16x16x32_bf16 v[44:47], v[128:131], v[160:163], v[44:47]
	v_mfma_f32_16x16x32_bf16 v[40:43], v[136:139], v[160:163], v[40:43]
	v_mfma_f32_16x16x32_bf16 v[36:39], v[128:131], v[168:171], v[36:39]
	v_mfma_f32_16x16x32_bf16 v[32:35], v[136:139], v[168:171], v[32:35]
	v_mfma_f32_16x16x32_bf16 v[60:63], v[132:135], v[148:151], v[60:63]
	v_mfma_f32_16x16x32_bf16 v[56:59], v[140:143], v[148:151], v[56:59]
	v_mfma_f32_16x16x32_bf16 v[52:55], v[132:135], v[156:159], v[52:55]
	v_mfma_f32_16x16x32_bf16 v[48:51], v[140:143], v[156:159], v[48:51]
	v_mfma_f32_16x16x32_bf16 v[44:47], v[132:135], v[164:167], v[44:47]
	v_mfma_f32_16x16x32_bf16 v[40:43], v[140:143], v[164:167], v[40:43]
	v_mfma_f32_16x16x32_bf16 v[36:39], v[132:135], v[172:175], v[36:39]
	v_mfma_f32_16x16x32_bf16 v[32:35], v[140:143], v[172:175], v[32:35]
	v_mfma_f32_16x16x32_bf16 v[28:31], v[176:179], v[144:147], v[28:31]
	v_mfma_f32_16x16x32_bf16 v[24:27], v[184:187], v[144:147], v[24:27]
	v_mfma_f32_16x16x32_bf16 v[20:23], v[176:179], v[152:155], v[20:23]
	v_mfma_f32_16x16x32_bf16 v[16:19], v[184:187], v[152:155], v[16:19]
	v_mfma_f32_16x16x32_bf16 v[12:15], v[176:179], v[160:163], v[12:15]
	v_mfma_f32_16x16x32_bf16 v[8:11], v[184:187], v[160:163], v[8:11]
	v_mfma_f32_16x16x32_bf16 v[4:7], v[176:179], v[168:171], v[4:7]
	v_mfma_f32_16x16x32_bf16 v[0:3], v[184:187], v[168:171], v[0:3]
	v_mfma_f32_16x16x32_bf16 v[28:31], v[180:183], v[148:151], v[28:31]
	v_mfma_f32_16x16x32_bf16 v[24:27], v[188:191], v[148:151], v[24:27]
	v_mfma_f32_16x16x32_bf16 v[20:23], v[180:183], v[156:159], v[20:23]
	v_mfma_f32_16x16x32_bf16 v[16:19], v[188:191], v[156:159], v[16:19]
	v_mfma_f32_16x16x32_bf16 v[12:15], v[180:183], v[164:167], v[12:15]
	v_mfma_f32_16x16x32_bf16 v[8:11], v[188:191], v[164:167], v[8:11]
	v_mfma_f32_16x16x32_bf16 v[4:7], v[180:183], v[172:175], v[4:7]
	v_mfma_f32_16x16x32_bf16 v[0:3], v[188:191], v[172:175], v[0:3]
	s_add_i32 s55, s55, 2
	s_add_u32 s44, s44, 0x100
	s_addc_u32 s45, s45, 0
	s_add_u32 s41, s41, 0x100
	s_addc_u32 s43, s43, 0
	s_cmp_gt_u32 s55, 13
	s_barrier
	s_cbranch_scc0 .LBB0_400
	s_cmp_lt_i32 s14, 2
	v_lshl_add_u32 v208, s15, 8, v244
	v_lshl_or_b32 v206, s54, 8, v246
	s_cselect_b64 s[8:9], -1, 0
	s_cmp_gt_i32 s14, 1
	v_mov_b64_e32 v[128:129], s[26:27]
	s_cselect_b64 s[92:93], -1, 0
	s_cmp_lg_u64 s[8:9], 0
	v_ashrrev_i32_e32 v207, 31, v206
	v_mad_i64_i32 v[128:129], s[6:7], v208, s58, v[128:129]
	s_addc_u32 s15, s14, 0
	s_lshl_b32 s46, s14, 11
	v_lshl_add_u64 v[128:129], v[206:207], 1, v[128:129]
	s_ashr_i32 s47, s46, 31
	v_lshl_add_u64 v[128:129], v[128:129], 0, s[34:35]
	v_lshl_add_u64 v[130:131], s[46:47], 1, v[128:129]
	global_load_dwordx4 v[188:191], v[130:131], off
	s_lshl_b32 s52, s15, 11
	s_ashr_i32 s53, s52, 31
	v_mov_b32_e32 v148, 0
	s_and_b64 vcc, exec, s[92:93]
	v_lshl_add_u64 v[128:129], s[52:53], 1, v[128:129]
	v_mov_b32_e32 v180, 0
	v_mov_b32_e32 v181, 0
	v_mov_b32_e32 v182, 0
	v_mov_b32_e32 v183, 0
	s_cbranch_vccnz .LBB0_403
	global_load_dwordx4 v[180:183], v[128:129], off

; #define PG8_STAGE(bufoff, gbase, voff) do { _Pragma("unroll") for (int _i = 0; _i < 2; ++_i) \
;         __builtin_amdgcn_global_load_lds((const unsigned*)((const char*)(gbase) + (voff)[_i]), (LAS unsigned*)(lds + (bufoff) + ldsw + _i * 8192), 16, 0, 0); } while (0)
; #define PG8_LDA(dst, b, h) do { _Pragma("unroll") for (int m = 0; m < 4; ++m) _Pragma("unroll") for (int k = 0; k < 2; ++k) dst[m][k] = *(const LAS bf16x8*)(lds + PG8_SA(b, h) + aoff + m * 2048 + k * 1024); } while (0)
; #define PG8_WAIT_V(n) asm volatile("s_waitcnt vmcnt(" #n ")" ::: "memory")
; #define PG8_WAIT_L(n) asm volatile("s_waitcnt lgkmcnt(" #n ")" ::: "memory")
; template <class Prog>
; __device__ __forceinline__ void gemm_phase(LAS unsigned char* lds, const int K, const Prog& S) {
;     ...
;         for (int t = 0; t < nt; t += 2) {
;             const bool last = (t == nt - 2);
;             const char* a1 = cA + (size_t)(t + 1) * kstep;
;             const char* a2 = last ? nA : cA + (size_t)(t + 2) * kstep; const char* b2 = last ? nB : cB + (size_t)(t + 2) * kstep;
;             const char* a3 = a2 + kstep; const char* b3 = b2 + kstep;
;             PG8_LDB(B0, 0, 0); PG8_SCHED; PG8_LDA(At, 0, 0); PG8_STAGE(PG8_SA(1, 1), a1 + hstep, voffA);
;             PG8_WAIT_L(8); PG8_BAR; PG8_WAIT_L(0); PG8_MMA(0, 0, At, B0); PG8_BAR; PG8_SCHED;
;             PG8_LDB(B1, 0, 1); PG8_STAGE(PG8_SB(0, 0), b2, voffB);
;             PG8_BAR; PG8_WAIT_L(0); PG8_MMA(0, 1, At, B1); PG8_BAR;
;             PG8_LDA(At, 0, 1); PG8_STAGE(PG8_SA(0, 0), a2, voffA);
;             PG8_BAR; PG8_WAIT_L(0); PG8_MMA(1, 0, At, B0); PG8_BAR; PG8_SCHED;
;             PG8_STAGE(PG8_SB(0, 1), b2 + hstep, voffB);
;             PG8_WAIT_V(6); PG8_BAR; PG8_MMA(1, 1, At, B1); PG8_BAR;
;             PG8_LDB(B0, 1, 0); PG8_SCHED; PG8_LDA(At, 1, 0); PG8_STAGE(PG8_SA(0, 1), a2 + hstep, voffA);
;             PG8_WAIT_L(8); PG8_BAR; PG8_WAIT_L(0); PG8_MMA(0, 0, At, B0); PG8_BAR; PG8_SCHED;
;             PG8_LDB(B1, 1, 1); PG8_STAGE(PG8_SB(1, 0), b3, voffB);
;             PG8_BAR; PG8_WAIT_L(0); PG8_MMA(0, 1, At, B1); PG8_BAR;
;             PG8_LDA(At, 1, 1); PG8_STAGE(PG8_SA(1, 0), a3, voffA);
;             PG8_BAR; PG8_WAIT_L(0); PG8_MMA(1, 0, At, B0); PG8_BAR; PG8_SCHED;
;             PG8_STAGE(PG8_SB(1, 1), b3 + hstep, voffB);
;             PG8_WAIT_V(6); PG8_BAR; PG8_MMA(1, 1, At, B1); PG8_BAR;
.LBB0_570:
	s_add_u32 s46, s46, 0x80080
	s_addc_u32 s47, s47, 0
	s_add_u32 s41, s52, 0x100
	s_addc_u32 s43, s53, 0
	s_mov_b32 s54, -2
	s_waitcnt lgkmcnt(0)
	s_waitcnt vmcnt(16)
	v_add_u32_e32 v202, 0x10000, v215
	s_add_u32 s52, s46, 0xfff80080
	s_addc_u32 s53, s47, -1
	s_cmp_eq_u32 s54, 28
	s_cselect_b32 s93, s7, s53
	s_cselect_b32 s92, s6, s52
	s_cselect_b32 s53, s45, s43
	s_cselect_b32 s52, s44, s41
	s_add_u32 vcc_lo, s46, 0xfff80000
	s_addc_u32 vcc_hi, s47, -1
	ds_read_b128 v[128:131], v202
	ds_read_b128 v[132:135], v202 offset:1024
	ds_read_b128 v[136:139], v202 offset:2048
	ds_read_b128 v[140:143], v202 offset:3072
	s_add_i32 m0, s75, 0x8000
	ds_read_b128 v[176:179], v202 offset:16384
	ds_read_b128 v[180:183], v202 offset:17408
	ds_read_b128 v[184:187], v202 offset:18432
	ds_read_b128 v[198:201], v202 offset:19456
	global_load_lds_dwordx4 v190, vcc
	s_add_i32 m0, s75, 0xa000
	ds_read_b128 v[144:147], v217
	ds_read_b128 v[148:151], v217 offset:1024
	ds_read_b128 v[152:155], v217 offset:2048
	ds_read_b128 v[156:159], v217 offset:3072
	global_load_lds_dwordx4 v196, vcc
	s_add_i32 m0, s75, 0xc000
	ds_read_b128 v[160:163], v217 offset:4096
	ds_read_b128 v[164:167], v217 offset:5120
	ds_read_b128 v[168:171], v217 offset:6144
	global_load_lds_dwordx4 v190, s[46:47]
	s_add_i32 m0, s75, 0xe000
	ds_read_b128 v[172:175], v217 offset:7168
	global_load_lds_dwordx4 v196, s[46:47]
	s_waitcnt lgkmcnt(0)
	s_barrier
	v_mfma_f32_16x16x32_bf16 v[124:127], v[128:131], v[144:147], 0
	v_mfma_f32_16x16x32_bf16 v[120:123], v[136:139], v[144:147], 0
	v_mfma_f32_16x16x32_bf16 v[108:111], v[128:131], v[152:155], 0
	v_mfma_f32_16x16x32_bf16 v[104:107], v[136:139], v[152:155], 0
	v_mfma_f32_16x16x32_bf16 v[92:95], v[128:131], v[160:163], 0
	v_mfma_f32_16x16x32_bf16 v[88:91], v[136:139], v[160:163], 0
	v_mfma_f32_16x16x32_bf16 v[76:79], v[128:131], v[168:171], 0
	v_mfma_f32_16x16x32_bf16 v[72:75], v[136:139], v[168:171], 0
	v_mfma_f32_16x16x32_bf16 v[124:127], v[132:135], v[148:151], v[124:127]
	v_mfma_f32_16x16x32_bf16 v[120:123], v[140:143], v[148:151], v[120:123]
	v_mfma_f32_16x16x32_bf16 v[108:111], v[132:135], v[156:159], v[108:111]
	v_mfma_f32_16x16x32_bf16 v[104:107], v[140:143], v[156:159], v[104:107]
	v_mfma_f32_16x16x32_bf16 v[92:95], v[132:135], v[164:167], v[92:95]
	v_mfma_f32_16x16x32_bf16 v[88:91], v[140:143], v[164:167], v[88:91]
	v_mfma_f32_16x16x32_bf16 v[76:79], v[132:135], v[172:175], v[76:79]
	v_mfma_f32_16x16x32_bf16 v[72:75], v[140:143], v[172:175], v[72:75]
	v_mfma_f32_16x16x32_bf16 v[116:119], v[176:179], v[144:147], 0
	v_mfma_f32_16x16x32_bf16 v[112:115], v[184:187], v[144:147], 0
	v_mfma_f32_16x16x32_bf16 v[100:103], v[176:179], v[152:155], 0
	v_mfma_f32_16x16x32_bf16 v[96:99], v[184:187], v[152:155], 0
	v_mfma_f32_16x16x32_bf16 v[84:87], v[176:179], v[160:163], 0
	v_mfma_f32_16x16x32_bf16 v[80:83], v[184:187], v[160:163], 0
	v_mfma_f32_16x16x32_bf16 v[68:71], v[176:179], v[168:171], 0
	v_mfma_f32_16x16x32_bf16 v[64:67], v[184:187], v[168:171], 0
	v_mfma_f32_16x16x32_bf16 v[116:119], v[180:183], v[148:151], v[116:119]
	v_mfma_f32_16x16x32_bf16 v[112:115], v[198:201], v[148:151], v[112:115]
	v_mfma_f32_16x16x32_bf16 v[100:103], v[180:183], v[156:159], v[100:103]
	v_mfma_f32_16x16x32_bf16 v[96:99], v[198:201], v[156:159], v[96:99]
	v_mfma_f32_16x16x32_bf16 v[84:87], v[180:183], v[164:167], v[84:87]
	v_mfma_f32_16x16x32_bf16 v[80:83], v[198:201], v[164:167], v[80:83]
	v_mfma_f32_16x16x32_bf16 v[68:71], v[180:183], v[172:175], v[68:71]
	v_mfma_f32_16x16x32_bf16 v[64:67], v[198:201], v[172:175], v[64:67]
	s_barrier
	s_add_i32 m0, s75, 0x10000
	ds_read_b128 v[144:147], v217 offset:16384
	ds_read_b128 v[148:151], v217 offset:17408
	global_load_lds_dwordx4 v192, s[52:53]
	s_add_i32 m0, s75, 0x12000
	ds_read_b128 v[152:155], v217 offset:18432
	ds_read_b128 v[156:159], v217 offset:19456
	global_load_lds_dwordx4 v188, s[52:53]
	s_add_i32 m0, s75, 0x14000
	s_add_u32 vcc_lo, s52, 0x80000
	s_addc_u32 vcc_hi, s53, 0
	ds_read_b128 v[160:163], v217 offset:20480
	ds_read_b128 v[164:167], v217 offset:21504
	global_load_lds_dwordx4 v192, vcc
	s_add_i32 m0, s75, 0x16000
	ds_read_b128 v[168:171], v217 offset:22528
	ds_read_b128 v[172:175], v217 offset:23552
	global_load_lds_dwordx4 v188, vcc
	s_waitcnt vmcnt(4) lgkmcnt(0)
	s_barrier
	v_mfma_f32_16x16x32_bf16 v[60:63], v[128:131], v[144:147], 0
	v_mfma_f32_16x16x32_bf16 v[56:59], v[136:139], v[144:147], 0
	v_mfma_f32_16x16x32_bf16 v[44:47], v[128:131], v[152:155], 0
	v_mfma_f32_16x16x32_bf16 v[40:43], v[136:139], v[152:155], 0
	v_mfma_f32_16x16x32_bf16 v[28:31], v[128:131], v[160:163], 0
	v_mfma_f32_16x16x32_bf16 v[24:27], v[136:139], v[160:163], 0
	v_mfma_f32_16x16x32_bf16 v[12:15], v[128:131], v[168:171], 0
	v_mfma_f32_16x16x32_bf16 v[8:11], v[136:139], v[168:171], 0
	v_mfma_f32_16x16x32_bf16 v[60:63], v[132:135], v[148:151], v[60:63]
	v_mfma_f32_16x16x32_bf16 v[56:59], v[140:143], v[148:151], v[56:59]
	v_mfma_f32_16x16x32_bf16 v[44:47], v[132:135], v[156:159], v[44:47]
	v_mfma_f32_16x16x32_bf16 v[40:43], v[140:143], v[156:159], v[40:43]
	v_mfma_f32_16x16x32_bf16 v[28:31], v[132:135], v[164:167], v[28:31]
	v_mfma_f32_16x16x32_bf16 v[24:27], v[140:143], v[164:167], v[24:27]
	v_mfma_f32_16x16x32_bf16 v[12:15], v[132:135], v[172:175], v[12:15]
	v_mfma_f32_16x16x32_bf16 v[8:11], v[140:143], v[172:175], v[8:11]
	v_mfma_f32_16x16x32_bf16 v[52:55], v[176:179], v[144:147], 0
	v_mfma_f32_16x16x32_bf16 v[48:51], v[184:187], v[144:147], 0
	v_mfma_f32_16x16x32_bf16 v[36:39], v[176:179], v[152:155], 0
	v_mfma_f32_16x16x32_bf16 v[32:35], v[184:187], v[152:155], 0
	v_mfma_f32_16x16x32_bf16 v[20:23], v[176:179], v[160:163], 0
	v_mfma_f32_16x16x32_bf16 v[16:19], v[184:187], v[160:163], 0
	v_mfma_f32_16x16x32_bf16 v[4:7], v[176:179], v[168:171], 0
	v_mfma_f32_16x16x32_bf16 v[0:3], v[184:187], v[168:171], 0
	v_mfma_f32_16x16x32_bf16 v[52:55], v[180:183], v[148:151], v[52:55]
	v_mfma_f32_16x16x32_bf16 v[48:51], v[198:201], v[148:151], v[48:51]
	v_mfma_f32_16x16x32_bf16 v[36:39], v[180:183], v[156:159], v[36:39]
	v_mfma_f32_16x16x32_bf16 v[32:35], v[198:201], v[156:159], v[32:35]
	v_mfma_f32_16x16x32_bf16 v[20:23], v[180:183], v[164:167], v[20:23]
	v_mfma_f32_16x16x32_bf16 v[16:19], v[198:201], v[164:167], v[16:19]
	v_mfma_f32_16x16x32_bf16 v[4:7], v[180:183], v[172:175], v[4:7]
	v_mfma_f32_16x16x32_bf16 v[0:3], v[198:201], v[172:175], v[0:3]
	s_barrier
; #define PG8_STAGE(bufoff, gbase, voff) do { _Pragma("unroll") for (int _i = 0; _i < 2; ++_i) \
;         __builtin_amdgcn_global_load_lds((const unsigned*)((const char*)(gbase) + (voff)[_i]), (LAS unsigned*)(lds + (bufoff) + ldsw + _i * 8192), 16, 0, 0); } while (0)
; #define PG8_LDA(dst, b, h) do { _Pragma("unroll") for (int m = 0; m < 4; ++m) _Pragma("unroll") for (int k = 0; k < 2; ++k) dst[m][k] = *(const LAS bf16x8*)(lds + PG8_SA(b, h) + aoff + m * 2048 + k * 1024); } while (0)
; #define PG8_WAIT_V(n) asm volatile("s_waitcnt vmcnt(" #n ")" ::: "memory")
; #define PG8_WAIT_L(n) asm volatile("s_waitcnt lgkmcnt(" #n ")" ::: "memory")
; template <class Prog>
; __device__ __forceinline__ void gemm_phase(LAS unsigned char* lds, const int K, const Prog& S) {
;     ...
;         for (int t = 0; t < nt; t += 2) {
;             const bool last = (t == nt - 2);
;             const char* a1 = cA + (size_t)(t + 1) * kstep;
;             const char* a2 = last ? nA : cA + (size_t)(t + 2) * kstep; const char* b2 = last ? nB : cB + (size_t)(t + 2) * kstep;
;             const char* a3 = a2 + kstep; const char* b3 = b2 + kstep;
;             PG8_LDB(B0, 0, 0); PG8_SCHED; PG8_LDA(At, 0, 0); PG8_STAGE(PG8_SA(1, 1), a1 + hstep, voffA);
;             PG8_WAIT_L(8); PG8_BAR; PG8_WAIT_L(0); PG8_MMA(0, 0, At, B0); PG8_BAR; PG8_SCHED;
;             PG8_LDB(B1, 0, 1); PG8_STAGE(PG8_SB(0, 0), b2, voffB);
;             PG8_BAR; PG8_WAIT_L(0); PG8_MMA(0, 1, At, B1); PG8_BAR;
;             PG8_LDA(At, 0, 1); PG8_STAGE(PG8_SA(0, 0), a2, voffA);
;             PG8_BAR; PG8_WAIT_L(0); PG8_MMA(1, 0, At, B0); PG8_BAR; PG8_SCHED;
;             PG8_STAGE(PG8_SB(0, 1), b2 + hstep, voffB);
;             PG8_WAIT_V(6); PG8_BAR; PG8_MMA(1, 1, At, B1); PG8_BAR;
;             PG8_LDB(B0, 1, 0); PG8_SCHED; PG8_LDA(At, 1, 0); PG8_STAGE(PG8_SA(0, 1), a2 + hstep, voffA);
;             PG8_WAIT_L(8); PG8_BAR; PG8_WAIT_L(0); PG8_MMA(0, 0, At, B0); PG8_BAR; PG8_SCHED;
;             PG8_LDB(B1, 1, 1); PG8_STAGE(PG8_SB(1, 0), b3, voffB);
;             PG8_BAR; PG8_WAIT_L(0); PG8_MMA(0, 1, At, B1); PG8_BAR;
;             PG8_LDA(At, 1, 1); PG8_STAGE(PG8_SA(1, 0), a3, voffA);
;             PG8_BAR; PG8_WAIT_L(0); PG8_MMA(1, 0, At, B0); PG8_BAR; PG8_SCHED;
;             PG8_STAGE(PG8_SB(1, 1), b3 + hstep, voffB);
;             PG8_WAIT_V(6); PG8_BAR; PG8_MMA(1, 1, At, B1); PG8_BAR;
	s_add_u32 s98, s92, 0x80000
	s_addc_u32 s99, s93, 0
	ds_read_b128 v[128:131], v202 offset:32768
	ds_read_b128 v[132:135], v202 offset:33792
	ds_read_b128 v[136:139], v202 offset:34816
	ds_read_b128 v[140:143], v202 offset:35840
	s_mov_b32 m0, s75
	ds_read_b128 v[176:179], v202 offset:49152
	ds_read_b128 v[180:183], v202 offset:50176
	ds_read_b128 v[184:187], v202 offset:51200
	ds_read_b128 v[198:201], v202 offset:52224
	global_load_lds_dwordx4 v192, s[92:93]
	s_add_i32 m0, s75, 0x2000
	ds_read_b128 v[144:147], v217 offset:32768
	ds_read_b128 v[148:151], v217 offset:33792
	ds_read_b128 v[152:155], v217 offset:34816
	ds_read_b128 v[156:159], v217 offset:35840
	global_load_lds_dwordx4 v188, s[92:93]
	s_add_i32 m0, s75, 0x4000
	ds_read_b128 v[160:163], v217 offset:36864
	ds_read_b128 v[164:167], v217 offset:37888
	ds_read_b128 v[168:171], v217 offset:38912
	global_load_lds_dwordx4 v192, s[98:99]
	s_add_i32 m0, s75, 0x6000
	ds_read_b128 v[172:175], v217 offset:39936
	global_load_lds_dwordx4 v188, s[98:99]
	s_waitcnt lgkmcnt(0)
	s_barrier
	v_mfma_f32_16x16x32_bf16 v[124:127], v[128:131], v[144:147], v[124:127]
	v_mfma_f32_16x16x32_bf16 v[120:123], v[136:139], v[144:147], v[120:123]
	v_mfma_f32_16x16x32_bf16 v[108:111], v[128:131], v[152:155], v[108:111]
	v_mfma_f32_16x16x32_bf16 v[104:107], v[136:139], v[152:155], v[104:107]
	v_mfma_f32_16x16x32_bf16 v[92:95], v[128:131], v[160:163], v[92:95]
	v_mfma_f32_16x16x32_bf16 v[88:91], v[136:139], v[160:163], v[88:91]
	v_mfma_f32_16x16x32_bf16 v[76:79], v[128:131], v[168:171], v[76:79]
	v_mfma_f32_16x16x32_bf16 v[72:75], v[136:139], v[168:171], v[72:75]
	v_mfma_f32_16x16x32_bf16 v[124:127], v[132:135], v[148:151], v[124:127]
	v_mfma_f32_16x16x32_bf16 v[120:123], v[140:143], v[148:151], v[120:123]
	v_mfma_f32_16x16x32_bf16 v[108:111], v[132:135], v[156:159], v[108:111]
	v_mfma_f32_16x16x32_bf16 v[104:107], v[140:143], v[156:159], v[104:107]
	v_mfma_f32_16x16x32_bf16 v[92:95], v[132:135], v[164:167], v[92:95]
	v_mfma_f32_16x16x32_bf16 v[88:91], v[140:143], v[164:167], v[88:91]
	v_mfma_f32_16x16x32_bf16 v[76:79], v[132:135], v[172:175], v[76:79]
	v_mfma_f32_16x16x32_bf16 v[72:75], v[140:143], v[172:175], v[72:75]
	v_mfma_f32_16x16x32_bf16 v[116:119], v[176:179], v[144:147], v[116:119]
	v_mfma_f32_16x16x32_bf16 v[112:115], v[184:187], v[144:147], v[112:115]
	v_mfma_f32_16x16x32_bf16 v[100:103], v[176:179], v[152:155], v[100:103]
	v_mfma_f32_16x16x32_bf16 v[96:99], v[184:187], v[152:155], v[96:99]
	v_mfma_f32_16x16x32_bf16 v[84:87], v[176:179], v[160:163], v[84:87]
	v_mfma_f32_16x16x32_bf16 v[80:83], v[184:187], v[160:163], v[80:83]
	v_mfma_f32_16x16x32_bf16 v[68:71], v[176:179], v[168:171], v[68:71]
	v_mfma_f32_16x16x32_bf16 v[64:67], v[184:187], v[168:171], v[64:67]
	v_mfma_f32_16x16x32_bf16 v[116:119], v[180:183], v[148:151], v[116:119]
	v_mfma_f32_16x16x32_bf16 v[112:115], v[198:201], v[148:151], v[112:115]
	v_mfma_f32_16x16x32_bf16 v[100:103], v[180:183], v[156:159], v[100:103]
	v_mfma_f32_16x16x32_bf16 v[96:99], v[198:201], v[156:159], v[96:99]
	v_mfma_f32_16x16x32_bf16 v[84:87], v[180:183], v[164:167], v[84:87]
	v_mfma_f32_16x16x32_bf16 v[80:83], v[198:201], v[164:167], v[80:83]
	v_mfma_f32_16x16x32_bf16 v[68:71], v[180:183], v[172:175], v[68:71]
	v_mfma_f32_16x16x32_bf16 v[64:67], v[198:201], v[172:175], v[64:67]
	s_barrier
	s_add_u32 s98, s52, 0x80
	s_addc_u32 s99, s53, 0
	s_add_i32 m0, s75, 0x18000
	ds_read_b128 v[144:147], v217 offset:49152
	ds_read_b128 v[148:151], v217 offset:50176
	global_load_lds_dwordx4 v192, s[98:99]
	s_add_i32 m0, s75, 0x1a000
	ds_read_b128 v[152:155], v217 offset:51200
	ds_read_b128 v[156:159], v217 offset:52224
	global_load_lds_dwordx4 v188, s[98:99]
	s_add_i32 m0, s75, 0x1c000
	s_add_u32 vcc_lo, s52, 0x80080
	s_addc_u32 vcc_hi, s53, 0
	ds_read_b128 v[160:163], v217 offset:53248
	ds_read_b128 v[164:167], v217 offset:54272
	global_load_lds_dwordx4 v192, vcc
	s_add_i32 m0, s75, 0x1e000
	ds_read_b128 v[168:171], v217 offset:55296
	ds_read_b128 v[172:175], v217 offset:56320
	global_load_lds_dwordx4 v188, vcc
	s_waitcnt vmcnt(4) lgkmcnt(0)
	s_barrier
	v_mfma_f32_16x16x32_bf16 v[60:63], v[128:131], v[144:147], v[60:63]
	v_mfma_f32_16x16x32_bf16 v[56:59], v[136:139], v[144:147], v[56:59]
	v_mfma_f32_16x16x32_bf16 v[44:47], v[128:131], v[152:155], v[44:47]
	v_mfma_f32_16x16x32_bf16 v[40:43], v[136:139], v[152:155], v[40:43]
	v_mfma_f32_16x16x32_bf16 v[28:31], v[128:131], v[160:163], v[28:31]
	v_mfma_f32_16x16x32_bf16 v[24:27], v[136:139], v[160:163], v[24:27]
	v_mfma_f32_16x16x32_bf16 v[12:15], v[128:131], v[168:171], v[12:15]
	v_mfma_f32_16x16x32_bf16 v[8:11], v[136:139], v[168:171], v[8:11]
	v_mfma_f32_16x16x32_bf16 v[60:63], v[132:135], v[148:151], v[60:63]
	v_mfma_f32_16x16x32_bf16 v[56:59], v[140:143], v[148:151], v[56:59]
	v_mfma_f32_16x16x32_bf16 v[44:47], v[132:135], v[156:159], v[44:47]
	v_mfma_f32_16x16x32_bf16 v[40:43], v[140:143], v[156:159], v[40:43]
	v_mfma_f32_16x16x32_bf16 v[28:31], v[132:135], v[164:167], v[28:31]
	v_mfma_f32_16x16x32_bf16 v[24:27], v[140:143], v[164:167], v[24:27]
	v_mfma_f32_16x16x32_bf16 v[12:15], v[132:135], v[172:175], v[12:15]
	v_mfma_f32_16x16x32_bf16 v[8:11], v[140:143], v[172:175], v[8:11]
	v_mfma_f32_16x16x32_bf16 v[52:55], v[176:179], v[144:147], v[52:55]
	v_mfma_f32_16x16x32_bf16 v[48:51], v[184:187], v[144:147], v[48:51]
	v_mfma_f32_16x16x32_bf16 v[36:39], v[176:179], v[152:155], v[36:39]
	v_mfma_f32_16x16x32_bf16 v[32:35], v[184:187], v[152:155], v[32:35]
	v_mfma_f32_16x16x32_bf16 v[20:23], v[176:179], v[160:163], v[20:23]
	v_mfma_f32_16x16x32_bf16 v[16:19], v[184:187], v[160:163], v[16:19]
	v_mfma_f32_16x16x32_bf16 v[4:7], v[176:179], v[168:171], v[4:7]
	v_mfma_f32_16x16x32_bf16 v[0:3], v[184:187], v[168:171], v[0:3]
	v_mfma_f32_16x16x32_bf16 v[52:55], v[180:183], v[148:151], v[52:55]
	v_mfma_f32_16x16x32_bf16 v[48:51], v[198:201], v[148:151], v[48:51]
	v_mfma_f32_16x16x32_bf16 v[36:39], v[180:183], v[156:159], v[36:39]
	v_mfma_f32_16x16x32_bf16 v[32:35], v[198:201], v[156:159], v[32:35]
	v_mfma_f32_16x16x32_bf16 v[20:23], v[180:183], v[164:167], v[20:23]
	v_mfma_f32_16x16x32_bf16 v[16:19], v[198:201], v[164:167], v[16:19]
	v_mfma_f32_16x16x32_bf16 v[4:7], v[180:183], v[172:175], v[4:7]
	v_mfma_f32_16x16x32_bf16 v[0:3], v[198:201], v[172:175], v[0:3]
	s_add_i32 s54, s54, 2
	s_add_u32 s46, s46, 0x100
	s_addc_u32 s47, s47, 0
	s_add_u32 s41, s41, 0x100
	s_addc_u32 s43, s43, 0
	s_cmp_gt_u32 s54, 29
	s_barrier
	.p2align 6
; #define PG8_STAGE(bufoff, gbase, voff) do { _Pragma("unroll") for (int _i = 0; _i < 2; ++_i) \
;         __builtin_amdgcn_global_load_lds((const unsigned*)((const char*)(gbase) + (voff)[_i]), (LAS unsigned*)(lds + (bufoff) + ldsw + _i * 8192), 16, 0, 0); } while (0)
; #define PG8_LDA(dst, b, h) do { _Pragma("unroll") for (int m = 0; m < 4; ++m) _Pragma("unroll") for (int k = 0; k < 2; ++k) dst[m][k] = *(const LAS bf16x8*)(lds + PG8_SA(b, h) + aoff + m * 2048 + k * 1024); } while (0)
; #define PG8_WAIT_V(n) asm volatile("s_waitcnt vmcnt(" #n ")" ::: "memory")
; #define PG8_WAIT_L(n) asm volatile("s_waitcnt lgkmcnt(" #n ")" ::: "memory")
; template <class Prog>
; __device__ __forceinline__ void gemm_phase(LAS unsigned char* lds, const int K, const Prog& S) {
;     ...
;         for (int t = 0; t < nt; t += 2) {
;             const bool last = (t == nt - 2);
;             const char* a1 = cA + (size_t)(t + 1) * kstep;
;             const char* a2 = last ? nA : cA + (size_t)(t + 2) * kstep; const char* b2 = last ? nB : cB + (size_t)(t + 2) * kstep;
;             const char* a3 = a2 + kstep; const char* b3 = b2 + kstep;
;             PG8_LDB(B0, 0, 0); PG8_SCHED; PG8_LDA(At, 0, 0); PG8_STAGE(PG8_SA(1, 1), a1 + hstep, voffA);
;             PG8_WAIT_L(8); PG8_BAR; PG8_WAIT_L(0); PG8_MMA(0, 0, At, B0); PG8_BAR; PG8_SCHED;
;             PG8_LDB(B1, 0, 1); PG8_STAGE(PG8_SB(0, 0), b2, voffB);
;             PG8_BAR; PG8_WAIT_L(0); PG8_MMA(0, 1, At, B1); PG8_BAR;
;             PG8_LDA(At, 0, 1); PG8_STAGE(PG8_SA(0, 0), a2, voffA);
;             PG8_BAR; PG8_WAIT_L(0); PG8_MMA(1, 0, At, B0); PG8_BAR; PG8_SCHED;
;             PG8_STAGE(PG8_SB(0, 1), b2 + hstep, voffB);
;             PG8_WAIT_V(6); PG8_BAR; PG8_MMA(1, 1, At, B1); PG8_BAR;
;             PG8_LDB(B0, 1, 0); PG8_SCHED; PG8_LDA(At, 1, 0); PG8_STAGE(PG8_SA(0, 1), a2 + hstep, voffA);
;             PG8_WAIT_L(8); PG8_BAR; PG8_WAIT_L(0); PG8_MMA(0, 0, At, B0); PG8_BAR; PG8_SCHED;
;             PG8_LDB(B1, 1, 1); PG8_STAGE(PG8_SB(1, 0), b3, voffB);
;             PG8_BAR; PG8_WAIT_L(0); PG8_MMA(0, 1, At, B1); PG8_BAR;
;             PG8_LDA(At, 1, 1); PG8_STAGE(PG8_SA(1, 0), a3, voffA);
;             PG8_BAR; PG8_WAIT_L(0); PG8_MMA(1, 0, At, B0); PG8_BAR; PG8_SCHED;
;             PG8_STAGE(PG8_SB(1, 1), b3 + hstep, voffB);
;             PG8_WAIT_V(6); PG8_BAR; PG8_MMA(1, 1, At, B1); PG8_BAR;
.LBB0_571:
	s_add_u32 s52, s46, 0xfff80080
	s_addc_u32 s53, s47, -1
	s_cmp_eq_u32 s54, 28
	s_cselect_b32 s93, s7, s53
	s_cselect_b32 s92, s6, s52
	s_cselect_b32 s53, s45, s43
	s_cselect_b32 s52, s44, s41
	s_add_u32 vcc_lo, s46, 0xfff80000
	s_addc_u32 vcc_hi, s47, -1
	ds_read_b128 v[128:131], v202
	ds_read_b128 v[132:135], v202 offset:1024
	ds_read_b128 v[136:139], v202 offset:2048
	ds_read_b128 v[140:143], v202 offset:3072
	s_add_i32 m0, s75, 0x8000
	ds_read_b128 v[176:179], v202 offset:16384
	ds_read_b128 v[180:183], v202 offset:17408
	ds_read_b128 v[184:187], v202 offset:18432
	ds_read_b128 v[198:201], v202 offset:19456
	global_load_lds_dwordx4 v190, vcc
	s_add_i32 m0, s75, 0xa000
	ds_read_b128 v[144:147], v217
	ds_read_b128 v[148:151], v217 offset:1024
	ds_read_b128 v[152:155], v217 offset:2048
	ds_read_b128 v[156:159], v217 offset:3072
	global_load_lds_dwordx4 v196, vcc
	s_add_i32 m0, s75, 0xc000
	ds_read_b128 v[160:163], v217 offset:4096
	ds_read_b128 v[164:167], v217 offset:5120
	ds_read_b128 v[168:171], v217 offset:6144
	global_load_lds_dwordx4 v190, s[46:47]
	s_add_i32 m0, s75, 0xe000
	ds_read_b128 v[172:175], v217 offset:7168
	global_load_lds_dwordx4 v196, s[46:47]
	s_waitcnt lgkmcnt(0)
	s_barrier
	v_mfma_f32_16x16x32_bf16 v[124:127], v[128:131], v[144:147], v[124:127]
	v_mfma_f32_16x16x32_bf16 v[120:123], v[136:139], v[144:147], v[120:123]
	v_mfma_f32_16x16x32_bf16 v[108:111], v[128:131], v[152:155], v[108:111]
	v_mfma_f32_16x16x32_bf16 v[104:107], v[136:139], v[152:155], v[104:107]
	v_mfma_f32_16x16x32_bf16 v[92:95], v[128:131], v[160:163], v[92:95]
	v_mfma_f32_16x16x32_bf16 v[88:91], v[136:139], v[160:163], v[88:91]
	v_mfma_f32_16x16x32_bf16 v[76:79], v[128:131], v[168:171], v[76:79]
	v_mfma_f32_16x16x32_bf16 v[72:75], v[136:139], v[168:171], v[72:75]
	v_mfma_f32_16x16x32_bf16 v[124:127], v[132:135], v[148:151], v[124:127]
	v_mfma_f32_16x16x32_bf16 v[120:123], v[140:143], v[148:151], v[120:123]
	v_mfma_f32_16x16x32_bf16 v[108:111], v[132:135], v[156:159], v[108:111]
	v_mfma_f32_16x16x32_bf16 v[104:107], v[140:143], v[156:159], v[104:107]
	v_mfma_f32_16x16x32_bf16 v[92:95], v[132:135], v[164:167], v[92:95]
	v_mfma_f32_16x16x32_bf16 v[88:91], v[140:143], v[164:167], v[88:91]
	v_mfma_f32_16x16x32_bf16 v[76:79], v[132:135], v[172:175], v[76:79]
	v_mfma_f32_16x16x32_bf16 v[72:75], v[140:143], v[172:175], v[72:75]
	v_mfma_f32_16x16x32_bf16 v[116:119], v[176:179], v[144:147], v[116:119]
	v_mfma_f32_16x16x32_bf16 v[112:115], v[184:187], v[144:147], v[112:115]
	v_mfma_f32_16x16x32_bf16 v[100:103], v[176:179], v[152:155], v[100:103]
	v_mfma_f32_16x16x32_bf16 v[96:99], v[184:187], v[152:155], v[96:99]
	v_mfma_f32_16x16x32_bf16 v[84:87], v[176:179], v[160:163], v[84:87]
	v_mfma_f32_16x16x32_bf16 v[80:83], v[184:187], v[160:163], v[80:83]
	v_mfma_f32_16x16x32_bf16 v[68:71], v[176:179], v[168:171], v[68:71]
	v_mfma_f32_16x16x32_bf16 v[64:67], v[184:187], v[168:171], v[64:67]
	v_mfma_f32_16x16x32_bf16 v[116:119], v[180:183], v[148:151], v[116:119]
	v_mfma_f32_16x16x32_bf16 v[112:115], v[198:201], v[148:151], v[112:115]
	v_mfma_f32_16x16x32_bf16 v[100:103], v[180:183], v[156:159], v[100:103]
	v_mfma_f32_16x16x32_bf16 v[96:99], v[198:201], v[156:159], v[96:99]
	v_mfma_f32_16x16x32_bf16 v[84:87], v[180:183], v[164:167], v[84:87]
	v_mfma_f32_16x16x32_bf16 v[80:83], v[198:201], v[164:167], v[80:83]
	v_mfma_f32_16x16x32_bf16 v[68:71], v[180:183], v[172:175], v[68:71]
	v_mfma_f32_16x16x32_bf16 v[64:67], v[198:201], v[172:175], v[64:67]
	s_barrier
	s_add_i32 m0, s75, 0x10000
	ds_read_b128 v[144:147], v217 offset:16384
	ds_read_b128 v[148:151], v217 offset:17408
	global_load_lds_dwordx4 v192, s[52:53]
	s_add_i32 m0, s75, 0x12000
	ds_read_b128 v[152:155], v217 offset:18432
	ds_read_b128 v[156:159], v217 offset:19456
	global_load_lds_dwordx4 v188, s[52:53]
	s_add_i32 m0, s75, 0x14000
	s_add_u32 vcc_lo, s52, 0x80000
	s_addc_u32 vcc_hi, s53, 0
	ds_read_b128 v[160:163], v217 offset:20480
	ds_read_b128 v[164:167], v217 offset:21504
	global_load_lds_dwordx4 v192, vcc
	s_add_i32 m0, s75, 0x16000
	ds_read_b128 v[168:171], v217 offset:22528
	ds_read_b128 v[172:175], v217 offset:23552
	global_load_lds_dwordx4 v188, vcc
	s_waitcnt vmcnt(4) lgkmcnt(0)
	s_barrier
	v_mfma_f32_16x16x32_bf16 v[60:63], v[128:131], v[144:147], v[60:63]
	v_mfma_f32_16x16x32_bf16 v[56:59], v[136:139], v[144:147], v[56:59]
	v_mfma_f32_16x16x32_bf16 v[44:47], v[128:131], v[152:155], v[44:47]
	v_mfma_f32_16x16x32_bf16 v[40:43], v[136:139], v[152:155], v[40:43]
	v_mfma_f32_16x16x32_bf16 v[28:31], v[128:131], v[160:163], v[28:31]
	v_mfma_f32_16x16x32_bf16 v[24:27], v[136:139], v[160:163], v[24:27]
	v_mfma_f32_16x16x32_bf16 v[12:15], v[128:131], v[168:171], v[12:15]
	v_mfma_f32_16x16x32_bf16 v[8:11], v[136:139], v[168:171], v[8:11]
	v_mfma_f32_16x16x32_bf16 v[60:63], v[132:135], v[148:151], v[60:63]
	v_mfma_f32_16x16x32_bf16 v[56:59], v[140:143], v[148:151], v[56:59]
	v_mfma_f32_16x16x32_bf16 v[44:47], v[132:135], v[156:159], v[44:47]
	v_mfma_f32_16x16x32_bf16 v[40:43], v[140:143], v[156:159], v[40:43]
	v_mfma_f32_16x16x32_bf16 v[28:31], v[132:135], v[164:167], v[28:31]
	v_mfma_f32_16x16x32_bf16 v[24:27], v[140:143], v[164:167], v[24:27]
	v_mfma_f32_16x16x32_bf16 v[12:15], v[132:135], v[172:175], v[12:15]
	v_mfma_f32_16x16x32_bf16 v[8:11], v[140:143], v[172:175], v[8:11]
	v_mfma_f32_16x16x32_bf16 v[52:55], v[176:179], v[144:147], v[52:55]
	v_mfma_f32_16x16x32_bf16 v[48:51], v[184:187], v[144:147], v[48:51]
	v_mfma_f32_16x16x32_bf16 v[36:39], v[176:179], v[152:155], v[36:39]
	v_mfma_f32_16x16x32_bf16 v[32:35], v[184:187], v[152:155], v[32:35]
	v_mfma_f32_16x16x32_bf16 v[20:23], v[176:179], v[160:163], v[20:23]
	v_mfma_f32_16x16x32_bf16 v[16:19], v[184:187], v[160:163], v[16:19]
	v_mfma_f32_16x16x32_bf16 v[4:7], v[176:179], v[168:171], v[4:7]
	v_mfma_f32_16x16x32_bf16 v[0:3], v[184:187], v[168:171], v[0:3]
	v_mfma_f32_16x16x32_bf16 v[52:55], v[180:183], v[148:151], v[52:55]
	v_mfma_f32_16x16x32_bf16 v[48:51], v[198:201], v[148:151], v[48:51]
	v_mfma_f32_16x16x32_bf16 v[36:39], v[180:183], v[156:159], v[36:39]
	v_mfma_f32_16x16x32_bf16 v[32:35], v[198:201], v[156:159], v[32:35]
	v_mfma_f32_16x16x32_bf16 v[20:23], v[180:183], v[164:167], v[20:23]
	v_mfma_f32_16x16x32_bf16 v[16:19], v[198:201], v[164:167], v[16:19]
	v_mfma_f32_16x16x32_bf16 v[4:7], v[180:183], v[172:175], v[4:7]
	v_mfma_f32_16x16x32_bf16 v[0:3], v[198:201], v[172:175], v[0:3]
	s_barrier
; #define PG8_STAGE(bufoff, gbase, voff) do { _Pragma("unroll") for (int _i = 0; _i < 2; ++_i) \
;         __builtin_amdgcn_global_load_lds((const unsigned*)((const char*)(gbase) + (voff)[_i]), (LAS unsigned*)(lds + (bufoff) + ldsw + _i * 8192), 16, 0, 0); } while (0)
; #define PG8_LDA(dst, b, h) do { _Pragma("unroll") for (int m = 0; m < 4; ++m) _Pragma("unroll") for (int k = 0; k < 2; ++k) dst[m][k] = *(const LAS bf16x8*)(lds + PG8_SA(b, h) + aoff + m * 2048 + k * 1024); } while (0)
; #define PG8_WAIT_V(n) asm volatile("s_waitcnt vmcnt(" #n ")" ::: "memory")
; #define PG8_WAIT_L(n) asm volatile("s_waitcnt lgkmcnt(" #n ")" ::: "memory")
; template <class Prog>
; __device__ __forceinline__ void gemm_phase(LAS unsigned char* lds, const int K, const Prog& S) {
;     ...
;         for (int t = 0; t < nt; t += 2) {
;             const bool last = (t == nt - 2);
;             const char* a1 = cA + (size_t)(t + 1) * kstep;
;             const char* a2 = last ? nA : cA + (size_t)(t + 2) * kstep; const char* b2 = last ? nB : cB + (size_t)(t + 2) * kstep;
;             const char* a3 = a2 + kstep; const char* b3 = b2 + kstep;
;             PG8_LDB(B0, 0, 0); PG8_SCHED; PG8_LDA(At, 0, 0); PG8_STAGE(PG8_SA(1, 1), a1 + hstep, voffA);
;             PG8_WAIT_L(8); PG8_BAR; PG8_WAIT_L(0); PG8_MMA(0, 0, At, B0); PG8_BAR; PG8_SCHED;
;             PG8_LDB(B1, 0, 1); PG8_STAGE(PG8_SB(0, 0), b2, voffB);
;             PG8_BAR; PG8_WAIT_L(0); PG8_MMA(0, 1, At, B1); PG8_BAR;
;             PG8_LDA(At, 0, 1); PG8_STAGE(PG8_SA(0, 0), a2, voffA);
;             PG8_BAR; PG8_WAIT_L(0); PG8_MMA(1, 0, At, B0); PG8_BAR; PG8_SCHED;
;             PG8_STAGE(PG8_SB(0, 1), b2 + hstep, voffB);
;             PG8_WAIT_V(6); PG8_BAR; PG8_MMA(1, 1, At, B1); PG8_BAR;
;             PG8_LDB(B0, 1, 0); PG8_SCHED; PG8_LDA(At, 1, 0); PG8_STAGE(PG8_SA(0, 1), a2 + hstep, voffA);
;             PG8_WAIT_L(8); PG8_BAR; PG8_WAIT_L(0); PG8_MMA(0, 0, At, B0); PG8_BAR; PG8_SCHED;
;             PG8_LDB(B1, 1, 1); PG8_STAGE(PG8_SB(1, 0), b3, voffB);
;             PG8_BAR; PG8_WAIT_L(0); PG8_MMA(0, 1, At, B1); PG8_BAR;
;             PG8_LDA(At, 1, 1); PG8_STAGE(PG8_SA(1, 0), a3, voffA);
;             PG8_BAR; PG8_WAIT_L(0); PG8_MMA(1, 0, At, B0); PG8_BAR; PG8_SCHED;
;             PG8_STAGE(PG8_SB(1, 1), b3 + hstep, voffB);
;             PG8_WAIT_V(6); PG8_BAR; PG8_MMA(1, 1, At, B1); PG8_BAR;
	s_add_u32 s98, s92, 0x80000
	s_addc_u32 s99, s93, 0
	ds_read_b128 v[128:131], v202 offset:32768
	ds_read_b128 v[132:135], v202 offset:33792
	ds_read_b128 v[136:139], v202 offset:34816
	ds_read_b128 v[140:143], v202 offset:35840
	s_mov_b32 m0, s75
	ds_read_b128 v[176:179], v202 offset:49152
	ds_read_b128 v[180:183], v202 offset:50176
	ds_read_b128 v[184:187], v202 offset:51200
	ds_read_b128 v[198:201], v202 offset:52224
	global_load_lds_dwordx4 v192, s[92:93]
	s_add_i32 m0, s75, 0x2000
	ds_read_b128 v[144:147], v217 offset:32768
	ds_read_b128 v[148:151], v217 offset:33792
	ds_read_b128 v[152:155], v217 offset:34816
	ds_read_b128 v[156:159], v217 offset:35840
	global_load_lds_dwordx4 v188, s[92:93]
	s_add_i32 m0, s75, 0x4000
	ds_read_b128 v[160:163], v217 offset:36864
	ds_read_b128 v[164:167], v217 offset:37888
	ds_read_b128 v[168:171], v217 offset:38912
	global_load_lds_dwordx4 v192, s[98:99]
	s_add_i32 m0, s75, 0x6000
	ds_read_b128 v[172:175], v217 offset:39936
	global_load_lds_dwordx4 v188, s[98:99]
	s_waitcnt lgkmcnt(0)
	s_barrier
	v_mfma_f32_16x16x32_bf16 v[124:127], v[128:131], v[144:147], v[124:127]
	v_mfma_f32_16x16x32_bf16 v[120:123], v[136:139], v[144:147], v[120:123]
	v_mfma_f32_16x16x32_bf16 v[108:111], v[128:131], v[152:155], v[108:111]
	v_mfma_f32_16x16x32_bf16 v[104:107], v[136:139], v[152:155], v[104:107]
	v_mfma_f32_16x16x32_bf16 v[92:95], v[128:131], v[160:163], v[92:95]
	v_mfma_f32_16x16x32_bf16 v[88:91], v[136:139], v[160:163], v[88:91]
	v_mfma_f32_16x16x32_bf16 v[76:79], v[128:131], v[168:171], v[76:79]
	v_mfma_f32_16x16x32_bf16 v[72:75], v[136:139], v[168:171], v[72:75]
	v_mfma_f32_16x16x32_bf16 v[124:127], v[132:135], v[148:151], v[124:127]
	v_mfma_f32_16x16x32_bf16 v[120:123], v[140:143], v[148:151], v[120:123]
	v_mfma_f32_16x16x32_bf16 v[108:111], v[132:135], v[156:159], v[108:111]
	v_mfma_f32_16x16x32_bf16 v[104:107], v[140:143], v[156:159], v[104:107]
	v_mfma_f32_16x16x32_bf16 v[92:95], v[132:135], v[164:167], v[92:95]
	v_mfma_f32_16x16x32_bf16 v[88:91], v[140:143], v[164:167], v[88:91]
	v_mfma_f32_16x16x32_bf16 v[76:79], v[132:135], v[172:175], v[76:79]
	v_mfma_f32_16x16x32_bf16 v[72:75], v[140:143], v[172:175], v[72:75]
	v_mfma_f32_16x16x32_bf16 v[116:119], v[176:179], v[144:147], v[116:119]
	v_mfma_f32_16x16x32_bf16 v[112:115], v[184:187], v[144:147], v[112:115]
	v_mfma_f32_16x16x32_bf16 v[100:103], v[176:179], v[152:155], v[100:103]
	v_mfma_f32_16x16x32_bf16 v[96:99], v[184:187], v[152:155], v[96:99]
	v_mfma_f32_16x16x32_bf16 v[84:87], v[176:179], v[160:163], v[84:87]
	v_mfma_f32_16x16x32_bf16 v[80:83], v[184:187], v[160:163], v[80:83]
	v_mfma_f32_16x16x32_bf16 v[68:71], v[176:179], v[168:171], v[68:71]
	v_mfma_f32_16x16x32_bf16 v[64:67], v[184:187], v[168:171], v[64:67]
	v_mfma_f32_16x16x32_bf16 v[116:119], v[180:183], v[148:151], v[116:119]
	v_mfma_f32_16x16x32_bf16 v[112:115], v[198:201], v[148:151], v[112:115]
	v_mfma_f32_16x16x32_bf16 v[100:103], v[180:183], v[156:159], v[100:103]
	v_mfma_f32_16x16x32_bf16 v[96:99], v[198:201], v[156:159], v[96:99]
	v_mfma_f32_16x16x32_bf16 v[84:87], v[180:183], v[164:167], v[84:87]
	v_mfma_f32_16x16x32_bf16 v[80:83], v[198:201], v[164:167], v[80:83]
	v_mfma_f32_16x16x32_bf16 v[68:71], v[180:183], v[172:175], v[68:71]
	v_mfma_f32_16x16x32_bf16 v[64:67], v[198:201], v[172:175], v[64:67]
	s_barrier
	s_add_u32 s98, s52, 0x80
	s_addc_u32 s99, s53, 0
	s_add_i32 m0, s75, 0x18000
	ds_read_b128 v[144:147], v217 offset:49152
	ds_read_b128 v[148:151], v217 offset:50176
	global_load_lds_dwordx4 v192, s[98:99]
	s_add_i32 m0, s75, 0x1a000
	ds_read_b128 v[152:155], v217 offset:51200
	ds_read_b128 v[156:159], v217 offset:52224
	global_load_lds_dwordx4 v188, s[98:99]
	s_add_i32 m0, s75, 0x1c000
	s_add_u32 vcc_lo, s52, 0x80080
	s_addc_u32 vcc_hi, s53, 0
	ds_read_b128 v[160:163], v217 offset:53248
	ds_read_b128 v[164:167], v217 offset:54272
	global_load_lds_dwordx4 v192, vcc
	s_add_i32 m0, s75, 0x1e000
	ds_read_b128 v[168:171], v217 offset:55296
	ds_read_b128 v[172:175], v217 offset:56320
	global_load_lds_dwordx4 v188, vcc
	s_waitcnt vmcnt(4) lgkmcnt(0)
	s_barrier
; template <class Prog>
; __device__ __forceinline__ void gemm_phase(LAS unsigned char* lds, const int K, const Prog& S) {
;     ...
;         for (int t = 0; t < nt; t += 2) {
;             const bool last = (t == nt - 2);
;             const char* a1 = cA + (size_t)(t + 1) * kstep;
;             const char* a2 = last ? nA : cA + (size_t)(t + 2) * kstep; const char* b2 = last ? nB : cB + (size_t)(t + 2) * kstep;
;             const char* a3 = a2 + kstep; const char* b3 = b2 + kstep;
;             PG8_LDB(B0, 0, 0); PG8_SCHED; PG8_LDA(At, 0, 0); PG8_STAGE(PG8_SA(1, 1), a1 + hstep, voffA);
;             PG8_WAIT_L(8); PG8_BAR; PG8_WAIT_L(0); PG8_MMA(0, 0, At, B0); PG8_BAR; PG8_SCHED;
;             PG8_LDB(B1, 0, 1); PG8_STAGE(PG8_SB(0, 0), b2, voffB);
;             PG8_BAR; PG8_WAIT_L(0); PG8_MMA(0, 1, At, B1); PG8_BAR;
;             PG8_LDA(At, 0, 1); PG8_STAGE(PG8_SA(0, 0), a2, voffA);
;             PG8_BAR; PG8_WAIT_L(0); PG8_MMA(1, 0, At, B0); PG8_BAR; PG8_SCHED;
;             PG8_STAGE(PG8_SB(0, 1), b2 + hstep, voffB);
;             PG8_WAIT_V(6); PG8_BAR; PG8_MMA(1, 1, At, B1); PG8_BAR;
;             PG8_LDB(B0, 1, 0); PG8_SCHED; PG8_LDA(At, 1, 0); PG8_STAGE(PG8_SA(0, 1), a2 + hstep, voffA);
;             PG8_WAIT_L(8); PG8_BAR; PG8_WAIT_L(0); PG8_MMA(0, 0, At, B0); PG8_BAR; PG8_SCHED;
;             PG8_LDB(B1, 1, 1); PG8_STAGE(PG8_SB(1, 0), b3, voffB);
;             PG8_BAR; PG8_WAIT_L(0); PG8_MMA(0, 1, At, B1); PG8_BAR;
;             PG8_LDA(At, 1, 1); PG8_STAGE(PG8_SA(1, 0), a3, voffA);
;             PG8_BAR; PG8_WAIT_L(0); PG8_MMA(1, 0, At, B0); PG8_BAR; PG8_SCHED;
;             PG8_STAGE(PG8_SB(1, 1), b3 + hstep, voffB);
;             PG8_WAIT_V(6); PG8_BAR; PG8_MMA(1, 1, At, B1); PG8_BAR;
;     __device__ __forceinline__ void epi(f32x4 (&acc)[2][2][4][2], const pg8::Unit& u, int wr, int wc, int fr, int fq) const {
;         const int row0 = u.pm * 256 + wr * 64 + fr, col0 = u.pn * 256 + wc * 32 + 4 * fq;
; #pragma unroll
;         for (int ai = 0; ai < 2; ++ai) {
;             f32x4 xo[4][2][2];
; #pragma unroll
;             for (int m = 0; m < 4; ++m)
; #pragma unroll
;                 for (int bj = 0; bj < 2; ++bj)
; #pragma unroll
;                     for (int n = 0; n < 2; ++n) xo[m][bj][n] = *(const f32x4*)(xin + (size_t)(row0 + ai * 128 + m * 16) * DM + col0 + bj * 128 + n * 16);
; #pragma unroll
;             for (int m = 0; m < 4; ++m) {
	v_mfma_f32_16x16x32_bf16 v[60:63], v[128:131], v[144:147], v[60:63]
	v_mfma_f32_16x16x32_bf16 v[56:59], v[136:139], v[144:147], v[56:59]
	v_mfma_f32_16x16x32_bf16 v[44:47], v[128:131], v[152:155], v[44:47]
	v_mfma_f32_16x16x32_bf16 v[40:43], v[136:139], v[152:155], v[40:43]
	v_mfma_f32_16x16x32_bf16 v[28:31], v[128:131], v[160:163], v[28:31]
	v_mfma_f32_16x16x32_bf16 v[24:27], v[136:139], v[160:163], v[24:27]
	v_mfma_f32_16x16x32_bf16 v[12:15], v[128:131], v[168:171], v[12:15]
	v_mfma_f32_16x16x32_bf16 v[8:11], v[136:139], v[168:171], v[8:11]
	v_mfma_f32_16x16x32_bf16 v[60:63], v[132:135], v[148:151], v[60:63]
	v_mfma_f32_16x16x32_bf16 v[56:59], v[140:143], v[148:151], v[56:59]
	v_mfma_f32_16x16x32_bf16 v[44:47], v[132:135], v[156:159], v[44:47]
	v_mfma_f32_16x16x32_bf16 v[40:43], v[140:143], v[156:159], v[40:43]
	v_mfma_f32_16x16x32_bf16 v[28:31], v[132:135], v[164:167], v[28:31]
	v_mfma_f32_16x16x32_bf16 v[24:27], v[140:143], v[164:167], v[24:27]
	v_mfma_f32_16x16x32_bf16 v[12:15], v[132:135], v[172:175], v[12:15]
	v_mfma_f32_16x16x32_bf16 v[8:11], v[140:143], v[172:175], v[8:11]
	v_mfma_f32_16x16x32_bf16 v[52:55], v[176:179], v[144:147], v[52:55]
	v_mfma_f32_16x16x32_bf16 v[48:51], v[184:187], v[144:147], v[48:51]
	v_mfma_f32_16x16x32_bf16 v[36:39], v[176:179], v[152:155], v[36:39]
	v_mfma_f32_16x16x32_bf16 v[32:35], v[184:187], v[152:155], v[32:35]
	v_mfma_f32_16x16x32_bf16 v[20:23], v[176:179], v[160:163], v[20:23]
	v_mfma_f32_16x16x32_bf16 v[16:19], v[184:187], v[160:163], v[16:19]
	v_mfma_f32_16x16x32_bf16 v[4:7], v[176:179], v[168:171], v[4:7]
	v_mfma_f32_16x16x32_bf16 v[0:3], v[184:187], v[168:171], v[0:3]
	v_mfma_f32_16x16x32_bf16 v[52:55], v[180:183], v[148:151], v[52:55]
	v_mfma_f32_16x16x32_bf16 v[48:51], v[198:201], v[148:151], v[48:51]
	v_mfma_f32_16x16x32_bf16 v[36:39], v[180:183], v[156:159], v[36:39]
	v_mfma_f32_16x16x32_bf16 v[32:35], v[198:201], v[156:159], v[32:35]
	v_mfma_f32_16x16x32_bf16 v[20:23], v[180:183], v[164:167], v[20:23]
	v_mfma_f32_16x16x32_bf16 v[16:19], v[198:201], v[164:167], v[16:19]
	v_mfma_f32_16x16x32_bf16 v[4:7], v[180:183], v[172:175], v[4:7]
	v_mfma_f32_16x16x32_bf16 v[0:3], v[198:201], v[172:175], v[0:3]
	s_add_i32 s54, s54, 2
	s_add_u32 s46, s46, 0x100
	s_addc_u32 s47, s47, 0
	s_add_u32 s41, s41, 0x100
	s_addc_u32 s43, s43, 0
	s_cmp_gt_u32 s54, 29
	s_barrier
	s_cbranch_scc0 .LBB0_571
	v_lshl_add_u32 v202, s80, 8, v214
	v_lshl_or_b32 v198, s73, 8, v216
	v_ashrrev_i32_e32 v199, 31, v198
	v_ashrrev_i32_e32 v203, 31, v202
	v_lshl_add_u64 v[200:201], v[198:199], 2, s[8:9]
	v_lshlrev_b64 v[128:129], 13, v[202:203]
	v_or_b32_e32 v208, 16, v202
	v_lshl_add_u64 v[128:129], v[200:201], 0, v[128:129]
	v_ashrrev_i32_e32 v209, 31, v208
	global_load_dwordx4 v[210:213], v[128:129], off
	global_load_dwordx4 v[184:187], v[128:129], off offset:64
	global_load_dwordx4 v[180:183], v[128:129], off offset:512
	global_load_dwordx4 v[176:179], v[128:129], off offset:576
	v_lshlrev_b64 v[128:129], 13, v[208:209]
	v_or_b32_e32 v206, 32, v202
	v_lshl_add_u64 v[128:129], v[200:201], 0, v[128:129]
	v_ashrrev_i32_e32 v207, 31, v206
	global_load_dwordx4 v[172:175], v[128:129], off
	global_load_dwordx4 v[168:171], v[128:129], off offset:64
	global_load_dwordx4 v[164:167], v[128:129], off offset:512
	global_load_dwordx4 v[160:163], v[128:129], off offset:576
	v_lshlrev_b64 v[128:129], 13, v[206:207]
	v_or_b32_e32 v204, 48, v202
	v_lshl_add_u64 v[128:129], v[200:201], 0, v[128:129]
	v_ashrrev_i32_e32 v205, 31, v204
	global_load_dwordx4 v[156:159], v[128:129], off
	global_load_dwordx4 v[152:155], v[128:129], off offset:64
	global_load_dwordx4 v[148:151], v[128:129], off offset:512
	global_load_dwordx4 v[144:147], v[128:129], off offset:576
	v_lshlrev_b64 v[128:129], 13, v[204:205]
	v_lshl_add_u64 v[128:129], v[200:201], 0, v[128:129]
	global_load_dwordx4 v[140:143], v[128:129], off
	global_load_dwordx4 v[136:139], v[128:129], off offset:64
	global_load_dwordx4 v[132:135], v[128:129], off offset:512
	s_nop 0
	global_load_dwordx4 v[128:131], v[128:129], off offset:576
	v_lshlrev_b64 v[218:219], 11, v[202:203]
	v_lshl_add_u64 v[218:219], v[218:219], 0, v[198:199]
	s_andn2_b64 vcc, exec, s[12:13]
	s_waitcnt vmcnt(0)
	v_pk_add_f32 v[126:127], v[126:127], v[212:213]
	v_cndmask_b32_e64 v212, 0, 1, s[12:13]
	v_pk_add_f32 v[124:125], v[124:125], v[210:211]
	v_lshl_add_u64 v[210:211], v[218:219], 2, s[48:49]
	v_cmp_ne_u32_e64 s[6:7], 1, v212
	v_lshl_add_u64 v[212:213], v[218:219], 1, s[20:21]
	global_store_dwordx4 v[210:211], v[124:127], off
	s_cbranch_vccnz .LBB0_574
	v_cvt_pk_bf16_f32 v218, v124, v125
	v_cvt_pk_bf16_f32 v219, v126, v127
	global_store_dwordx2 v[212:213], v[218:219], off
